# non-temporal (nt) hint on the GEMM epilogue output stores, on top of v91
# baseline (speedup 1.0000x reference)
.LBB0_201:
	v_lshlrev_b32_e32 v148, 1, v158
	v_mov_b32_e32 v149, v2
	v_lshl_add_u64 v[180:181], s[28:29], 0, v[148:149]
	v_mad_i64_i32 v[148:149], s[28:29], s62, v172, 0
	v_lshl_add_u64 v[148:149], v[148:149], 1, v[180:181]
	v_cvt_pk_bf16_f32 v150, v184, v185
	v_cvt_pk_bf16_f32 v151, v182, v183
	global_store_dwordx2 v[148:149], v[150:151], off nt
	v_cvt_pk_bf16_f32 v150, v188, v189
	v_cvt_pk_bf16_f32 v151, v186, v187
	global_store_dwordx2 v[148:149], v[150:151], off offset:32 nt
	v_cvt_pk_bf16_f32 v150, v192, v193
	v_cvt_pk_bf16_f32 v151, v190, v191
	global_store_dwordx2 v[148:149], v[150:151], off offset:64 nt
	v_cvt_pk_bf16_f32 v150, v196, v197
	v_cvt_pk_bf16_f32 v151, v194, v195
	global_store_dwordx2 v[148:149], v[150:151], off offset:96 nt
	s_nop 0
	v_cndmask_b32_e64 v149, 0, 1, s[66:67]
	v_cmp_ne_u32_e64 s[40:41], 1, v149
	s_andn2_b64 vcc, exec, s[66:67]
	s_nop 1
	v_fmamk_f32 v148, v211, 0x3a800000, v202
	v_rsq_f32_e32 v148, v148
	s_nop 0
	v_pk_mul_f32 v[184:185], v[114:115], v[148:149] op_sel_hi:[1,0]
	v_pk_mul_f32 v[188:189], v[112:113], v[148:149] op_sel_hi:[1,0]
	v_pk_mul_f32 v[182:183], v[110:111], v[148:149] op_sel_hi:[1,0]
	v_pk_mul_f32 v[186:187], v[108:109], v[148:149] op_sel_hi:[1,0]
	v_pk_mul_f32 v[190:191], v[106:107], v[148:149] op_sel_hi:[1,0]
	v_pk_mul_f32 v[192:193], v[104:105], v[148:149] op_sel_hi:[1,0]
	v_pk_mul_f32 v[194:195], v[102:103], v[148:149] op_sel_hi:[1,0]
	v_pk_mul_f32 v[196:197], v[100:101], v[148:149] op_sel_hi:[1,0]
	s_cbranch_vccnz .LBB0_203
	v_pk_mul_f32 v[148:149], v[184:185], v[184:185]
	v_pk_mul_f32 v[150:151], v[188:189], v[188:189]
	v_mov_b32_e32 v153, v149
	v_mov_b32_e32 v152, v150
	v_pk_mov_b32 v[148:149], v[150:151], v[148:149] op_sel:[1,0]
	v_pk_mul_f32 v[150:151], v[182:183], v[182:183]
	v_pk_add_f32 v[148:149], v[148:149], v[152:153]
	v_pk_mul_f32 v[152:153], v[186:187], v[186:187]
	v_pk_add_f32 v[148:149], v[148:149], v[148:149] op_sel_hi:[0,1]
	v_mov_b32_e32 v154, v152
	v_mov_b32_e32 v155, v151
	v_pk_mov_b32 v[150:151], v[152:153], v[150:151] op_sel:[1,0]
	v_mul_f32_e32 v148, v192, v192
	v_pk_add_f32 v[150:151], v[150:151], v[154:155]
	v_pk_fma_f32 v[152:153], v[192:193], v[192:193], v[148:149] op_sel_hi:[1,1,0]
	v_mul_f32_e32 v148, v190, v190
	v_pk_add_f32 v[150:151], v[150:151], v[150:151] op_sel_hi:[0,1]
	v_pk_fma_f32 v[154:155], v[190:191], v[190:191], v[148:149] op_sel_hi:[1,1,0]
	v_mul_f32_e32 v152, v196, v196
	v_mul_f32_e32 v154, v197, v197
	v_mul_f32_e32 v148, v194, v194
	v_mul_f32_e32 v150, v195, v195
	v_pk_add_f32 v[152:153], v[152:153], v[154:155]
	v_pk_add_f32 v[148:149], v[148:149], v[150:151]
	v_and_b32_e32 v150, 64, v204
	v_pk_add_f32 v[148:149], v[152:153], v[148:149]
	v_add_u32_e32 v150, 64, v150
	v_add_f32_e32 v148, v148, v149
	v_xor_b32_e32 v149, 16, v204
	v_cmp_lt_i32_e32 vcc, v149, v150
	s_lshl_b32 s26, s24, 6
	v_lshl_add_u64 v[152:153], v[162:163], 0, s[26:27]
	v_cndmask_b32_e32 v149, v204, v149, vcc
	v_lshlrev_b32_e32 v149, 2, v149
	ds_bpermute_b32 v149, v149, v148
	global_load_dwordx4 v[152:155], v[152:153], off
	s_mov_b32 s28, s64
	s_mov_b32 s29, s64
	s_waitcnt lgkmcnt(0)
	v_add_f32_e32 v148, v148, v149
	v_xor_b32_e32 v149, 32, v204
	v_cmp_lt_i32_e32 vcc, v149, v150
	s_nop 1
	v_cndmask_b32_e32 v149, v204, v149, vcc
	v_lshlrev_b32_e32 v149, 2, v149
	ds_bpermute_b32 v149, v149, v148
	s_waitcnt lgkmcnt(0)
	v_add_f32_e32 v148, v148, v149
	v_fmamk_f32 v148, v148, 0x3c800000, v202
	v_rsq_f32_e32 v198, v148
	v_lshl_add_u64 v[148:149], v[160:161], 0, s[26:27]
	global_load_dwordx4 v[148:151], v[148:149], off
	global_load_dwordx4 v[218:221], v[164:165], off offset:1024
	global_load_dwordx4 v[222:225], v[166:167], off offset:1024
	v_pk_mul_f32 v[184:185], v[184:185], v[198:199] op_sel_hi:[1,0]
	s_nop 0
	v_pk_mul_f32 v[206:207], v[146:147], v[184:185]
	v_pk_mul_f32 v[182:183], v[182:183], v[198:199] op_sel_hi:[1,0]
	v_pk_mul_f32 v[184:185], v[186:187], v[198:199] op_sel_hi:[1,0]
	v_pk_mul_f32 v[188:189], v[188:189], v[198:199] op_sel_hi:[1,0]
	v_pk_mul_f32 v[186:187], v[140:141], v[184:185]
	v_pk_mul_f32 v[182:183], v[142:143], v[182:183]
	v_pk_mul_f32 v[208:209], v[144:145], v[188:189]
	v_pk_mul_f32 v[192:193], v[192:193], v[198:199] op_sel_hi:[1,0]
	v_pk_mul_f32 v[190:191], v[190:191], v[198:199] op_sel_hi:[1,0]
	s_waitcnt vmcnt(3)
	v_pk_mul_f32 v[184:185], v[154:155], v[182:183]
	v_pk_mul_f32 v[188:189], v[152:153], v[186:187]
	s_waitcnt vmcnt(2)
	v_pk_fma_f32 v[184:185], v[150:151], v[206:207], v[184:185] neg_lo:[0,0,1] neg_hi:[0,0,1]
	v_pk_fma_f32 v[188:189], v[148:149], v[208:209], v[188:189] neg_lo:[0,0,1] neg_hi:[0,0,1]
	v_pk_mul_f32 v[150:151], v[150:151], v[182:183]
	v_pk_mul_f32 v[148:149], v[148:149], v[186:187]
	v_pk_fma_f32 v[150:151], v[154:155], v[206:207], v[150:151]
	v_pk_fma_f32 v[148:149], v[152:153], v[208:209], v[148:149]
	v_pk_mul_f32 v[182:183], s[28:29], v[150:151]
	v_pk_mul_f32 v[186:187], s[64:65], v[148:149]
	s_nop 0
	v_pk_mul_f32 v[206:207], v[138:139], v[190:191]
	v_pk_mul_f32 v[208:209], v[136:137], v[192:193]
	v_pk_mul_f32 v[190:191], v[194:195], v[198:199] op_sel_hi:[1,0]
	v_pk_mul_f32 v[192:193], v[196:197], v[198:199] op_sel_hi:[1,0]
	v_pk_mul_f32 v[196:197], v[134:135], v[190:191]
	v_pk_mul_f32 v[194:195], v[132:133], v[192:193]
	v_pk_mul_f32 v[184:185], s[28:29], v[184:185]
	v_pk_mul_f32 v[188:189], s[64:65], v[188:189]
	s_waitcnt vmcnt(0)
	v_pk_mul_f32 v[190:191], v[224:225], v[196:197]
	v_pk_mul_f32 v[192:193], v[222:223], v[194:195]
	v_pk_fma_f32 v[190:191], v[220:221], v[206:207], v[190:191] neg_lo:[0,0,1] neg_hi:[0,0,1]
	v_pk_fma_f32 v[192:193], v[218:219], v[208:209], v[192:193] neg_lo:[0,0,1] neg_hi:[0,0,1]
	v_pk_mul_f32 v[150:151], v[220:221], v[196:197]
	v_pk_mul_f32 v[148:149], v[218:219], v[194:195]
	v_pk_fma_f32 v[150:151], v[224:225], v[206:207], v[150:151]
	v_pk_fma_f32 v[148:149], v[222:223], v[208:209], v[148:149]
	v_pk_mul_f32 v[190:191], s[28:29], v[190:191]
	v_pk_mul_f32 v[192:193], s[64:65], v[192:193]
	v_pk_mul_f32 v[194:195], s[28:29], v[150:151]
	v_pk_mul_f32 v[196:197], s[64:65], v[148:149]
.LBB0_203:
	v_or_b32_e32 v148, 16, v172
	v_mad_i64_i32 v[148:149], s[28:29], s62, v148, 0
	v_lshl_add_u64 v[148:149], v[148:149], 1, v[180:181]
	v_cvt_pk_bf16_f32 v150, v188, v189
	v_cvt_pk_bf16_f32 v151, v184, v185
	global_store_dwordx2 v[148:149], v[150:151], off nt
	v_cvt_pk_bf16_f32 v150, v186, v187
	v_cvt_pk_bf16_f32 v151, v182, v183
	global_store_dwordx2 v[148:149], v[150:151], off offset:32 nt
	v_cvt_pk_bf16_f32 v150, v192, v193
	v_cvt_pk_bf16_f32 v151, v190, v191
	global_store_dwordx2 v[148:149], v[150:151], off offset:64 nt
	v_cvt_pk_bf16_f32 v150, v196, v197
	v_cvt_pk_bf16_f32 v151, v194, v195
	global_store_dwordx2 v[148:149], v[150:151], off offset:96 nt
	s_nop 0
	s_and_b64 vcc, exec, s[40:41]
	s_nop 1
	v_fmamk_f32 v148, v212, 0x3a800000, v202
	v_rsq_f32_e32 v148, v148
	s_nop 0
	v_pk_mul_f32 v[184:185], v[98:99], v[148:149] op_sel_hi:[1,0]
	v_pk_mul_f32 v[188:189], v[96:97], v[148:149] op_sel_hi:[1,0]
	v_pk_mul_f32 v[182:183], v[94:95], v[148:149] op_sel_hi:[1,0]
	v_pk_mul_f32 v[186:187], v[92:93], v[148:149] op_sel_hi:[1,0]
	v_pk_mul_f32 v[190:191], v[90:91], v[148:149] op_sel_hi:[1,0]
	v_pk_mul_f32 v[192:193], v[88:89], v[148:149] op_sel_hi:[1,0]
	v_pk_mul_f32 v[194:195], v[86:87], v[148:149] op_sel_hi:[1,0]
	v_pk_mul_f32 v[196:197], v[84:85], v[148:149] op_sel_hi:[1,0]
	s_cbranch_vccnz .LBB0_205
	v_pk_mul_f32 v[148:149], v[184:185], v[184:185]
	v_pk_mul_f32 v[150:151], v[188:189], v[188:189]
	v_mov_b32_e32 v153, v149
	v_mov_b32_e32 v152, v150
	v_pk_mov_b32 v[148:149], v[150:151], v[148:149] op_sel:[1,0]
	v_pk_mul_f32 v[150:151], v[182:183], v[182:183]
	v_pk_add_f32 v[148:149], v[148:149], v[152:153]
	v_pk_mul_f32 v[152:153], v[186:187], v[186:187]
	v_pk_add_f32 v[148:149], v[148:149], v[148:149] op_sel_hi:[0,1]
	v_mov_b32_e32 v154, v152
	v_mov_b32_e32 v155, v151
	v_pk_mov_b32 v[150:151], v[152:153], v[150:151] op_sel:[1,0]
	v_mul_f32_e32 v148, v192, v192
	v_pk_add_f32 v[150:151], v[150:151], v[154:155]
	v_pk_fma_f32 v[152:153], v[192:193], v[192:193], v[148:149] op_sel_hi:[1,1,0]
	v_mul_f32_e32 v148, v190, v190
	v_pk_add_f32 v[150:151], v[150:151], v[150:151] op_sel_hi:[0,1]
	v_pk_fma_f32 v[154:155], v[190:191], v[190:191], v[148:149] op_sel_hi:[1,1,0]
	v_mul_f32_e32 v152, v196, v196
	v_mul_f32_e32 v154, v197, v197
	v_mul_f32_e32 v148, v194, v194
	v_mul_f32_e32 v150, v195, v195
	v_pk_add_f32 v[152:153], v[152:153], v[154:155]
	v_pk_add_f32 v[148:149], v[148:149], v[150:151]
	v_and_b32_e32 v150, 64, v204
	v_pk_add_f32 v[148:149], v[152:153], v[148:149]
	v_add_u32_e32 v150, 64, v150
	v_add_f32_e32 v148, v148, v149
	v_xor_b32_e32 v149, 16, v204
	v_cmp_lt_i32_e32 vcc, v149, v150
	s_lshl_b32 s26, s24, 6
	v_lshl_add_u64 v[152:153], v[162:163], 0, s[26:27]
	v_cndmask_b32_e32 v149, v204, v149, vcc
	v_lshlrev_b32_e32 v149, 2, v149
	ds_bpermute_b32 v149, v149, v148
	global_load_dwordx4 v[152:155], v[152:153], off
	s_mov_b32 s28, s64
	s_mov_b32 s29, s64
	s_waitcnt lgkmcnt(0)
	v_add_f32_e32 v148, v148, v149
	v_xor_b32_e32 v149, 32, v204
	v_cmp_lt_i32_e32 vcc, v149, v150
	s_nop 1
	v_cndmask_b32_e32 v149, v204, v149, vcc
	v_lshlrev_b32_e32 v149, 2, v149
	ds_bpermute_b32 v149, v149, v148
	s_waitcnt lgkmcnt(0)
	v_add_f32_e32 v148, v148, v149
	v_fmamk_f32 v148, v148, 0x3c800000, v202
	v_rsq_f32_e32 v198, v148
	v_lshl_add_u64 v[148:149], v[160:161], 0, s[26:27]
	global_load_dwordx4 v[148:151], v[148:149], off
	global_load_dwordx4 v[218:221], v[164:165], off offset:2048
	global_load_dwordx4 v[222:225], v[166:167], off offset:2048
	v_pk_mul_f32 v[184:185], v[184:185], v[198:199] op_sel_hi:[1,0]
	s_nop 0
	v_pk_mul_f32 v[206:207], v[146:147], v[184:185]
	v_pk_mul_f32 v[182:183], v[182:183], v[198:199] op_sel_hi:[1,0]
	v_pk_mul_f32 v[184:185], v[186:187], v[198:199] op_sel_hi:[1,0]
	v_pk_mul_f32 v[188:189], v[188:189], v[198:199] op_sel_hi:[1,0]
	v_pk_mul_f32 v[186:187], v[140:141], v[184:185]
	v_pk_mul_f32 v[182:183], v[142:143], v[182:183]
	v_pk_mul_f32 v[208:209], v[144:145], v[188:189]
	v_pk_mul_f32 v[192:193], v[192:193], v[198:199] op_sel_hi:[1,0]
	v_pk_mul_f32 v[190:191], v[190:191], v[198:199] op_sel_hi:[1,0]
	s_waitcnt vmcnt(3)
	v_pk_mul_f32 v[184:185], v[154:155], v[182:183]
	v_pk_mul_f32 v[188:189], v[152:153], v[186:187]
	s_waitcnt vmcnt(2)
	v_pk_fma_f32 v[184:185], v[150:151], v[206:207], v[184:185] neg_lo:[0,0,1] neg_hi:[0,0,1]
	v_pk_fma_f32 v[188:189], v[148:149], v[208:209], v[188:189] neg_lo:[0,0,1] neg_hi:[0,0,1]
	v_pk_mul_f32 v[150:151], v[150:151], v[182:183]
	v_pk_mul_f32 v[148:149], v[148:149], v[186:187]
	v_pk_fma_f32 v[150:151], v[154:155], v[206:207], v[150:151]
	v_pk_fma_f32 v[148:149], v[152:153], v[208:209], v[148:149]
	v_pk_mul_f32 v[182:183], s[28:29], v[150:151]
	v_pk_mul_f32 v[186:187], s[64:65], v[148:149]
	s_nop 0
	v_pk_mul_f32 v[206:207], v[138:139], v[190:191]
	v_pk_mul_f32 v[208:209], v[136:137], v[192:193]
	v_pk_mul_f32 v[190:191], v[194:195], v[198:199] op_sel_hi:[1,0]
	v_pk_mul_f32 v[192:193], v[196:197], v[198:199] op_sel_hi:[1,0]
	v_pk_mul_f32 v[196:197], v[134:135], v[190:191]
	v_pk_mul_f32 v[194:195], v[132:133], v[192:193]
	v_pk_mul_f32 v[184:185], s[28:29], v[184:185]
	v_pk_mul_f32 v[188:189], s[64:65], v[188:189]
	s_waitcnt vmcnt(0)
	v_pk_mul_f32 v[190:191], v[224:225], v[196:197]
	v_pk_mul_f32 v[192:193], v[222:223], v[194:195]
	v_pk_fma_f32 v[190:191], v[220:221], v[206:207], v[190:191] neg_lo:[0,0,1] neg_hi:[0,0,1]
	v_pk_fma_f32 v[192:193], v[218:219], v[208:209], v[192:193] neg_lo:[0,0,1] neg_hi:[0,0,1]
	v_pk_mul_f32 v[150:151], v[220:221], v[196:197]
	v_pk_mul_f32 v[148:149], v[218:219], v[194:195]
	v_pk_fma_f32 v[150:151], v[224:225], v[206:207], v[150:151]
	v_pk_fma_f32 v[148:149], v[222:223], v[208:209], v[148:149]
	v_pk_mul_f32 v[190:191], s[28:29], v[190:191]
	v_pk_mul_f32 v[192:193], s[64:65], v[192:193]
	v_pk_mul_f32 v[194:195], s[28:29], v[150:151]
	v_pk_mul_f32 v[196:197], s[64:65], v[148:149]
.LBB0_205:
	v_or_b32_e32 v148, 32, v172
	v_mad_i64_i32 v[148:149], s[28:29], s62, v148, 0
	v_lshl_add_u64 v[148:149], v[148:149], 1, v[180:181]
	v_cvt_pk_bf16_f32 v150, v188, v189
	v_cvt_pk_bf16_f32 v151, v184, v185
	global_store_dwordx2 v[148:149], v[150:151], off nt
	v_cvt_pk_bf16_f32 v150, v186, v187
	v_cvt_pk_bf16_f32 v151, v182, v183
	global_store_dwordx2 v[148:149], v[150:151], off offset:32 nt
	v_cvt_pk_bf16_f32 v150, v192, v193
	v_cvt_pk_bf16_f32 v151, v190, v191
	global_store_dwordx2 v[148:149], v[150:151], off offset:64 nt
	v_cvt_pk_bf16_f32 v150, v196, v197
	v_cvt_pk_bf16_f32 v151, v194, v195
	global_store_dwordx2 v[148:149], v[150:151], off offset:96 nt
	s_nop 0
	s_and_b64 vcc, exec, s[40:41]
	s_nop 1
	v_fmamk_f32 v148, v213, 0x3a800000, v202
	v_rsq_f32_e32 v148, v148
	s_nop 0
	v_pk_mul_f32 v[184:185], v[82:83], v[148:149] op_sel_hi:[1,0]
	v_pk_mul_f32 v[188:189], v[80:81], v[148:149] op_sel_hi:[1,0]
	v_pk_mul_f32 v[182:183], v[78:79], v[148:149] op_sel_hi:[1,0]
	v_pk_mul_f32 v[186:187], v[76:77], v[148:149] op_sel_hi:[1,0]
	v_pk_mul_f32 v[190:191], v[74:75], v[148:149] op_sel_hi:[1,0]
	v_pk_mul_f32 v[192:193], v[72:73], v[148:149] op_sel_hi:[1,0]
	v_pk_mul_f32 v[194:195], v[70:71], v[148:149] op_sel_hi:[1,0]
	v_pk_mul_f32 v[196:197], v[68:69], v[148:149] op_sel_hi:[1,0]
	s_cbranch_vccnz .LBB0_207
	v_pk_mul_f32 v[148:149], v[184:185], v[184:185]
	v_pk_mul_f32 v[150:151], v[188:189], v[188:189]
	v_mov_b32_e32 v153, v149
	v_mov_b32_e32 v152, v150
	v_pk_mov_b32 v[148:149], v[150:151], v[148:149] op_sel:[1,0]
	v_pk_mul_f32 v[150:151], v[182:183], v[182:183]
	v_pk_add_f32 v[148:149], v[148:149], v[152:153]
	v_pk_mul_f32 v[152:153], v[186:187], v[186:187]
	v_pk_add_f32 v[148:149], v[148:149], v[148:149] op_sel_hi:[0,1]
	v_mov_b32_e32 v154, v152
	v_mov_b32_e32 v155, v151
	v_pk_mov_b32 v[150:151], v[152:153], v[150:151] op_sel:[1,0]
	v_mul_f32_e32 v148, v192, v192
	v_pk_add_f32 v[150:151], v[150:151], v[154:155]
	v_pk_fma_f32 v[152:153], v[192:193], v[192:193], v[148:149] op_sel_hi:[1,1,0]
	v_mul_f32_e32 v148, v190, v190
	v_pk_add_f32 v[150:151], v[150:151], v[150:151] op_sel_hi:[0,1]
	v_pk_fma_f32 v[154:155], v[190:191], v[190:191], v[148:149] op_sel_hi:[1,1,0]
	v_mul_f32_e32 v152, v196, v196
	v_mul_f32_e32 v154, v197, v197
	v_mul_f32_e32 v148, v194, v194
	v_mul_f32_e32 v150, v195, v195
	v_pk_add_f32 v[152:153], v[152:153], v[154:155]
	v_pk_add_f32 v[148:149], v[148:149], v[150:151]
	v_and_b32_e32 v150, 64, v204
	v_pk_add_f32 v[148:149], v[152:153], v[148:149]
	v_add_u32_e32 v150, 64, v150
	v_add_f32_e32 v148, v148, v149
	v_xor_b32_e32 v149, 16, v204
	v_cmp_lt_i32_e32 vcc, v149, v150
	s_lshl_b32 s26, s24, 6
	v_lshl_add_u64 v[152:153], v[162:163], 0, s[26:27]
	v_cndmask_b32_e32 v149, v204, v149, vcc
	v_lshlrev_b32_e32 v149, 2, v149
	ds_bpermute_b32 v149, v149, v148
	global_load_dwordx4 v[152:155], v[152:153], off
	s_mov_b32 s28, s64
	s_mov_b32 s29, s64
	s_waitcnt lgkmcnt(0)
	v_add_f32_e32 v148, v148, v149
	v_xor_b32_e32 v149, 32, v204
	v_cmp_lt_i32_e32 vcc, v149, v150
	s_nop 1
	v_cndmask_b32_e32 v149, v204, v149, vcc
	v_lshlrev_b32_e32 v149, 2, v149
	ds_bpermute_b32 v149, v149, v148
	s_waitcnt lgkmcnt(0)
	v_add_f32_e32 v148, v148, v149
	v_fmamk_f32 v148, v148, 0x3c800000, v202
	v_rsq_f32_e32 v198, v148
	v_lshl_add_u64 v[148:149], v[160:161], 0, s[26:27]
	global_load_dwordx4 v[148:151], v[148:149], off
	global_load_dwordx4 v[218:221], v[164:165], off offset:3072
	global_load_dwordx4 v[222:225], v[166:167], off offset:3072
	v_pk_mul_f32 v[184:185], v[184:185], v[198:199] op_sel_hi:[1,0]
	s_nop 0
	v_pk_mul_f32 v[206:207], v[146:147], v[184:185]
	v_pk_mul_f32 v[182:183], v[182:183], v[198:199] op_sel_hi:[1,0]
	v_pk_mul_f32 v[184:185], v[186:187], v[198:199] op_sel_hi:[1,0]
	v_pk_mul_f32 v[188:189], v[188:189], v[198:199] op_sel_hi:[1,0]
	v_pk_mul_f32 v[186:187], v[140:141], v[184:185]
	v_pk_mul_f32 v[182:183], v[142:143], v[182:183]
	v_pk_mul_f32 v[208:209], v[144:145], v[188:189]
	v_pk_mul_f32 v[192:193], v[192:193], v[198:199] op_sel_hi:[1,0]
	v_pk_mul_f32 v[190:191], v[190:191], v[198:199] op_sel_hi:[1,0]
	s_waitcnt vmcnt(3)
	v_pk_mul_f32 v[184:185], v[154:155], v[182:183]
	v_pk_mul_f32 v[188:189], v[152:153], v[186:187]
	s_waitcnt vmcnt(2)
	v_pk_fma_f32 v[184:185], v[150:151], v[206:207], v[184:185] neg_lo:[0,0,1] neg_hi:[0,0,1]
	v_pk_fma_f32 v[188:189], v[148:149], v[208:209], v[188:189] neg_lo:[0,0,1] neg_hi:[0,0,1]
	v_pk_mul_f32 v[150:151], v[150:151], v[182:183]
	v_pk_mul_f32 v[148:149], v[148:149], v[186:187]
	v_pk_fma_f32 v[150:151], v[154:155], v[206:207], v[150:151]
	v_pk_fma_f32 v[148:149], v[152:153], v[208:209], v[148:149]
	v_pk_mul_f32 v[182:183], s[28:29], v[150:151]
	v_pk_mul_f32 v[186:187], s[64:65], v[148:149]
	s_nop 0
	v_pk_mul_f32 v[206:207], v[138:139], v[190:191]
	v_pk_mul_f32 v[208:209], v[136:137], v[192:193]
	v_pk_mul_f32 v[190:191], v[194:195], v[198:199] op_sel_hi:[1,0]
	v_pk_mul_f32 v[192:193], v[196:197], v[198:199] op_sel_hi:[1,0]
	v_pk_mul_f32 v[196:197], v[134:135], v[190:191]
	v_pk_mul_f32 v[194:195], v[132:133], v[192:193]
	v_pk_mul_f32 v[184:185], s[28:29], v[184:185]
	v_pk_mul_f32 v[188:189], s[64:65], v[188:189]
	s_waitcnt vmcnt(0)
	v_pk_mul_f32 v[190:191], v[224:225], v[196:197]
	v_pk_mul_f32 v[192:193], v[222:223], v[194:195]
	v_pk_fma_f32 v[190:191], v[220:221], v[206:207], v[190:191] neg_lo:[0,0,1] neg_hi:[0,0,1]
	v_pk_fma_f32 v[192:193], v[218:219], v[208:209], v[192:193] neg_lo:[0,0,1] neg_hi:[0,0,1]
	v_pk_mul_f32 v[150:151], v[220:221], v[196:197]
	v_pk_mul_f32 v[148:149], v[218:219], v[194:195]
	v_pk_fma_f32 v[150:151], v[224:225], v[206:207], v[150:151]
	v_pk_fma_f32 v[148:149], v[222:223], v[208:209], v[148:149]
	v_pk_mul_f32 v[190:191], s[28:29], v[190:191]
	v_pk_mul_f32 v[192:193], s[64:65], v[192:193]
	v_pk_mul_f32 v[194:195], s[28:29], v[150:151]
	v_pk_mul_f32 v[196:197], s[64:65], v[148:149]
.LBB0_207:
	v_or_b32_e32 v148, 48, v172
	v_mad_i64_i32 v[148:149], s[24:25], s62, v148, 0
	v_lshl_add_u64 v[148:149], v[148:149], 1, v[180:181]
	v_cvt_pk_bf16_f32 v150, v188, v189
	v_cvt_pk_bf16_f32 v151, v184, v185
	global_store_dwordx2 v[148:149], v[150:151], off nt
	v_cvt_pk_bf16_f32 v150, v186, v187
	v_cvt_pk_bf16_f32 v151, v182, v183
	global_store_dwordx2 v[148:149], v[150:151], off offset:32 nt
	v_cvt_pk_bf16_f32 v150, v192, v193
	v_cvt_pk_bf16_f32 v151, v190, v191
	global_store_dwordx2 v[148:149], v[150:151], off offset:64 nt
	v_cvt_pk_bf16_f32 v150, v196, v197
	v_cvt_pk_bf16_f32 v151, v194, v195
	global_store_dwordx2 v[148:149], v[150:151], off offset:96 nt
	s_nop 0
	v_add_u32_e32 v173, 0x80, v172
	v_bfe_u32 v149, v173, 6, 8
	s_and_b64 vcc, exec, s[40:41]
	v_lshlrev_b32_e32 v182, 6, v149
	s_nop 1
	v_fmamk_f32 v148, v214, 0x3a800000, v202
	v_rsq_f32_e32 v148, v148
	s_nop 0
	v_pk_mul_f32 v[186:187], v[66:67], v[148:149] op_sel_hi:[1,0]
	v_pk_mul_f32 v[190:191], v[64:65], v[148:149] op_sel_hi:[1,0]
	v_pk_mul_f32 v[184:185], v[62:63], v[148:149] op_sel_hi:[1,0]
	v_pk_mul_f32 v[188:189], v[60:61], v[148:149] op_sel_hi:[1,0]
	v_pk_mul_f32 v[192:193], v[58:59], v[148:149] op_sel_hi:[1,0]
	v_pk_mul_f32 v[194:195], v[56:57], v[148:149] op_sel_hi:[1,0]
	v_pk_mul_f32 v[196:197], v[54:55], v[148:149] op_sel_hi:[1,0]
	v_pk_mul_f32 v[198:199], v[52:53], v[148:149] op_sel_hi:[1,0]
	s_cbranch_vccnz .LBB0_209
	v_pk_mul_f32 v[148:149], v[186:187], v[186:187]
	v_pk_mul_f32 v[150:151], v[190:191], v[190:191]
	v_mov_b32_e32 v153, v149
	v_mov_b32_e32 v152, v150
	v_pk_mov_b32 v[148:149], v[150:151], v[148:149] op_sel:[1,0]
	v_pk_mul_f32 v[150:151], v[184:185], v[184:185]
	v_pk_add_f32 v[148:149], v[148:149], v[152:153]
	v_pk_mul_f32 v[152:153], v[188:189], v[188:189]
	v_pk_add_f32 v[148:149], v[148:149], v[148:149] op_sel_hi:[0,1]
	v_mov_b32_e32 v154, v152
	v_mov_b32_e32 v155, v151
	v_pk_mov_b32 v[150:151], v[152:153], v[150:151] op_sel:[1,0]
	v_mul_f32_e32 v148, v194, v194
	v_pk_add_f32 v[150:151], v[150:151], v[154:155]
	v_pk_fma_f32 v[152:153], v[194:195], v[194:195], v[148:149] op_sel_hi:[1,1,0]
	v_mul_f32_e32 v148, v192, v192
	v_pk_add_f32 v[150:151], v[150:151], v[150:151] op_sel_hi:[0,1]
	v_pk_fma_f32 v[154:155], v[192:193], v[192:193], v[148:149] op_sel_hi:[1,1,0]
	v_mul_f32_e32 v152, v198, v198
	v_mul_f32_e32 v154, v199, v199
	v_mul_f32_e32 v148, v196, v196
	v_mul_f32_e32 v150, v197, v197
	v_pk_add_f32 v[152:153], v[152:153], v[154:155]
	v_pk_add_f32 v[148:149], v[148:149], v[150:151]
	v_and_b32_e32 v150, 64, v204
	v_pk_add_f32 v[148:149], v[152:153], v[148:149]
	v_add_u32_e32 v150, 64, v150
	v_add_f32_e32 v148, v148, v149
	v_xor_b32_e32 v149, 16, v204
	v_cmp_lt_i32_e32 vcc, v149, v150
	v_mov_b32_e32 v183, v2
	v_lshl_add_u64 v[152:153], v[162:163], 0, v[182:183]
	v_cndmask_b32_e32 v149, v204, v149, vcc
	v_lshlrev_b32_e32 v149, 2, v149
	ds_bpermute_b32 v149, v149, v148
	global_load_dwordx4 v[152:155], v[152:153], off
	s_mov_b32 s28, s64
	s_mov_b32 s29, s64
	s_waitcnt lgkmcnt(0)
	v_add_f32_e32 v148, v148, v149
	v_xor_b32_e32 v149, 32, v204
	v_cmp_lt_i32_e32 vcc, v149, v150
	s_nop 1
	v_cndmask_b32_e32 v149, v204, v149, vcc
	v_lshlrev_b32_e32 v149, 2, v149
	ds_bpermute_b32 v149, v149, v148
	s_waitcnt lgkmcnt(0)
	v_add_f32_e32 v148, v148, v149
	v_fmamk_f32 v148, v148, 0x3c800000, v202
	v_rsq_f32_e32 v200, v148
	v_lshl_add_u64 v[148:149], v[160:161], 0, v[182:183]
	global_load_dwordx4 v[148:151], v[148:149], off
	global_load_dwordx4 v[218:221], v[164:165], off
	global_load_dwordx4 v[222:225], v[166:167], off
	v_pk_mul_f32 v[186:187], v[186:187], v[200:201] op_sel_hi:[1,0]
	s_nop 0
	v_pk_mul_f32 v[206:207], v[146:147], v[186:187]
	v_pk_mul_f32 v[184:185], v[184:185], v[200:201] op_sel_hi:[1,0]
	v_pk_mul_f32 v[186:187], v[188:189], v[200:201] op_sel_hi:[1,0]
	v_pk_mul_f32 v[190:191], v[190:191], v[200:201] op_sel_hi:[1,0]
	v_pk_mul_f32 v[188:189], v[140:141], v[186:187]
	v_pk_mul_f32 v[184:185], v[142:143], v[184:185]
	v_pk_mul_f32 v[208:209], v[144:145], v[190:191]
	v_pk_mul_f32 v[194:195], v[194:195], v[200:201] op_sel_hi:[1,0]
	v_pk_mul_f32 v[192:193], v[192:193], v[200:201] op_sel_hi:[1,0]
	s_waitcnt vmcnt(3)
	v_pk_mul_f32 v[186:187], v[154:155], v[184:185]
	v_pk_mul_f32 v[190:191], v[152:153], v[188:189]
	s_waitcnt vmcnt(2)
	v_pk_fma_f32 v[186:187], v[150:151], v[206:207], v[186:187] neg_lo:[0,0,1] neg_hi:[0,0,1]
	v_pk_fma_f32 v[190:191], v[148:149], v[208:209], v[190:191] neg_lo:[0,0,1] neg_hi:[0,0,1]
	v_pk_mul_f32 v[150:151], v[150:151], v[184:185]
	v_pk_mul_f32 v[148:149], v[148:149], v[188:189]
	v_pk_fma_f32 v[150:151], v[154:155], v[206:207], v[150:151]
	v_pk_fma_f32 v[148:149], v[152:153], v[208:209], v[148:149]
	v_pk_mul_f32 v[184:185], s[28:29], v[150:151]
	v_pk_mul_f32 v[188:189], s[64:65], v[148:149]
	s_nop 0
	v_pk_mul_f32 v[206:207], v[138:139], v[192:193]
	v_pk_mul_f32 v[208:209], v[136:137], v[194:195]
	v_pk_mul_f32 v[192:193], v[196:197], v[200:201] op_sel_hi:[1,0]
	v_pk_mul_f32 v[194:195], v[198:199], v[200:201] op_sel_hi:[1,0]
	v_pk_mul_f32 v[198:199], v[134:135], v[192:193]
	v_pk_mul_f32 v[196:197], v[132:133], v[194:195]
	v_pk_mul_f32 v[186:187], s[28:29], v[186:187]
	v_pk_mul_f32 v[190:191], s[64:65], v[190:191]
	s_waitcnt vmcnt(0)
	v_pk_mul_f32 v[192:193], v[224:225], v[198:199]
	v_pk_mul_f32 v[194:195], v[222:223], v[196:197]
	v_pk_fma_f32 v[192:193], v[220:221], v[206:207], v[192:193] neg_lo:[0,0,1] neg_hi:[0,0,1]
	v_pk_fma_f32 v[194:195], v[218:219], v[208:209], v[194:195] neg_lo:[0,0,1] neg_hi:[0,0,1]
	v_pk_mul_f32 v[150:151], v[220:221], v[198:199]
	v_pk_mul_f32 v[148:149], v[218:219], v[196:197]
	v_pk_fma_f32 v[150:151], v[224:225], v[206:207], v[150:151]
	v_pk_fma_f32 v[148:149], v[222:223], v[208:209], v[148:149]
	v_pk_mul_f32 v[192:193], s[28:29], v[192:193]
	v_pk_mul_f32 v[194:195], s[64:65], v[194:195]
	v_pk_mul_f32 v[196:197], s[28:29], v[150:151]
	v_pk_mul_f32 v[198:199], s[64:65], v[148:149]
.LBB0_209:
	v_mad_i64_i32 v[148:149], s[24:25], s62, v173, 0
	v_lshl_add_u64 v[148:149], v[148:149], 1, v[180:181]
	v_cvt_pk_bf16_f32 v150, v190, v191
	v_cvt_pk_bf16_f32 v151, v186, v187
	global_store_dwordx2 v[148:149], v[150:151], off nt
	v_cvt_pk_bf16_f32 v150, v188, v189
	v_cvt_pk_bf16_f32 v151, v184, v185
	global_store_dwordx2 v[148:149], v[150:151], off offset:32 nt
	v_cvt_pk_bf16_f32 v150, v194, v195
	v_cvt_pk_bf16_f32 v151, v192, v193
	global_store_dwordx2 v[148:149], v[150:151], off offset:64 nt
	v_cvt_pk_bf16_f32 v150, v198, v199
	v_cvt_pk_bf16_f32 v151, v196, v197
	global_store_dwordx2 v[148:149], v[150:151], off offset:96 nt
	s_nop 0
	s_and_b64 vcc, exec, s[40:41]
	s_nop 1
	v_fmamk_f32 v148, v215, 0x3a800000, v202
	v_rsq_f32_e32 v148, v148
	s_nop 0
	v_pk_mul_f32 v[186:187], v[50:51], v[148:149] op_sel_hi:[1,0]
	v_pk_mul_f32 v[190:191], v[48:49], v[148:149] op_sel_hi:[1,0]
	v_pk_mul_f32 v[184:185], v[46:47], v[148:149] op_sel_hi:[1,0]
	v_pk_mul_f32 v[188:189], v[44:45], v[148:149] op_sel_hi:[1,0]
	v_pk_mul_f32 v[192:193], v[42:43], v[148:149] op_sel_hi:[1,0]
	v_pk_mul_f32 v[194:195], v[40:41], v[148:149] op_sel_hi:[1,0]
	v_pk_mul_f32 v[196:197], v[38:39], v[148:149] op_sel_hi:[1,0]
	v_pk_mul_f32 v[198:199], v[36:37], v[148:149] op_sel_hi:[1,0]
	s_cbranch_vccnz .LBB0_211
	v_pk_mul_f32 v[148:149], v[186:187], v[186:187]
	v_pk_mul_f32 v[150:151], v[190:191], v[190:191]
	v_mov_b32_e32 v153, v149
	v_mov_b32_e32 v152, v150
	v_pk_mov_b32 v[148:149], v[150:151], v[148:149] op_sel:[1,0]
	v_pk_mul_f32 v[150:151], v[184:185], v[184:185]
	v_pk_add_f32 v[148:149], v[148:149], v[152:153]
	v_pk_mul_f32 v[152:153], v[188:189], v[188:189]
	v_pk_add_f32 v[148:149], v[148:149], v[148:149] op_sel_hi:[0,1]
	v_mov_b32_e32 v154, v152
	v_mov_b32_e32 v155, v151
	v_pk_mov_b32 v[150:151], v[152:153], v[150:151] op_sel:[1,0]
	v_mul_f32_e32 v148, v194, v194
	v_pk_add_f32 v[150:151], v[150:151], v[154:155]
	v_pk_fma_f32 v[152:153], v[194:195], v[194:195], v[148:149] op_sel_hi:[1,1,0]
	v_mul_f32_e32 v148, v192, v192
	v_pk_add_f32 v[150:151], v[150:151], v[150:151] op_sel_hi:[0,1]
	v_pk_fma_f32 v[154:155], v[192:193], v[192:193], v[148:149] op_sel_hi:[1,1,0]
	v_mul_f32_e32 v152, v198, v198
	v_mul_f32_e32 v154, v199, v199
	v_mul_f32_e32 v148, v196, v196
	v_mul_f32_e32 v150, v197, v197
	v_pk_add_f32 v[152:153], v[152:153], v[154:155]
	v_pk_add_f32 v[148:149], v[148:149], v[150:151]
	v_and_b32_e32 v150, 64, v204
	v_pk_add_f32 v[148:149], v[152:153], v[148:149]
	v_add_u32_e32 v150, 64, v150
	v_add_f32_e32 v148, v148, v149
	v_xor_b32_e32 v149, 16, v204
	v_cmp_lt_i32_e32 vcc, v149, v150
	v_mov_b32_e32 v183, v2
	v_lshl_add_u64 v[152:153], v[162:163], 0, v[182:183]
	v_cndmask_b32_e32 v149, v204, v149, vcc
	v_lshlrev_b32_e32 v149, 2, v149
	ds_bpermute_b32 v149, v149, v148
	global_load_dwordx4 v[152:155], v[152:153], off
	s_mov_b32 s28, s64
	s_mov_b32 s29, s64
	s_waitcnt lgkmcnt(0)
	v_add_f32_e32 v148, v148, v149
	v_xor_b32_e32 v149, 32, v204
	v_cmp_lt_i32_e32 vcc, v149, v150
	s_nop 1
	v_cndmask_b32_e32 v149, v204, v149, vcc
	v_lshlrev_b32_e32 v149, 2, v149
	ds_bpermute_b32 v149, v149, v148
	s_waitcnt lgkmcnt(0)
	v_add_f32_e32 v148, v148, v149
	v_fmamk_f32 v148, v148, 0x3c800000, v202
	v_rsq_f32_e32 v200, v148
	v_lshl_add_u64 v[148:149], v[160:161], 0, v[182:183]
	global_load_dwordx4 v[148:151], v[148:149], off
	global_load_dwordx4 v[218:221], v[164:165], off offset:1024
	global_load_dwordx4 v[222:225], v[166:167], off offset:1024
	v_pk_mul_f32 v[186:187], v[186:187], v[200:201] op_sel_hi:[1,0]
	s_nop 0
	v_pk_mul_f32 v[206:207], v[146:147], v[186:187]
	v_pk_mul_f32 v[184:185], v[184:185], v[200:201] op_sel_hi:[1,0]
	v_pk_mul_f32 v[186:187], v[188:189], v[200:201] op_sel_hi:[1,0]
	v_pk_mul_f32 v[190:191], v[190:191], v[200:201] op_sel_hi:[1,0]
	v_pk_mul_f32 v[188:189], v[140:141], v[186:187]
	v_pk_mul_f32 v[184:185], v[142:143], v[184:185]
	v_pk_mul_f32 v[208:209], v[144:145], v[190:191]
	v_pk_mul_f32 v[194:195], v[194:195], v[200:201] op_sel_hi:[1,0]
	v_pk_mul_f32 v[192:193], v[192:193], v[200:201] op_sel_hi:[1,0]
	s_waitcnt vmcnt(3)
	v_pk_mul_f32 v[186:187], v[154:155], v[184:185]
	v_pk_mul_f32 v[190:191], v[152:153], v[188:189]
	s_waitcnt vmcnt(2)
	v_pk_fma_f32 v[186:187], v[150:151], v[206:207], v[186:187] neg_lo:[0,0,1] neg_hi:[0,0,1]
	v_pk_fma_f32 v[190:191], v[148:149], v[208:209], v[190:191] neg_lo:[0,0,1] neg_hi:[0,0,1]
	v_pk_mul_f32 v[150:151], v[150:151], v[184:185]
	v_pk_mul_f32 v[148:149], v[148:149], v[188:189]
	v_pk_fma_f32 v[150:151], v[154:155], v[206:207], v[150:151]
	v_pk_fma_f32 v[148:149], v[152:153], v[208:209], v[148:149]
	v_pk_mul_f32 v[184:185], s[28:29], v[150:151]
	v_pk_mul_f32 v[188:189], s[64:65], v[148:149]
	s_nop 0
	v_pk_mul_f32 v[206:207], v[138:139], v[192:193]
	v_pk_mul_f32 v[208:209], v[136:137], v[194:195]
	v_pk_mul_f32 v[192:193], v[196:197], v[200:201] op_sel_hi:[1,0]
	v_pk_mul_f32 v[194:195], v[198:199], v[200:201] op_sel_hi:[1,0]
	v_pk_mul_f32 v[198:199], v[134:135], v[192:193]
	v_pk_mul_f32 v[196:197], v[132:133], v[194:195]
	v_pk_mul_f32 v[186:187], s[28:29], v[186:187]
	v_pk_mul_f32 v[190:191], s[64:65], v[190:191]
	s_waitcnt vmcnt(0)
	v_pk_mul_f32 v[192:193], v[224:225], v[198:199]
	v_pk_mul_f32 v[194:195], v[222:223], v[196:197]
	v_pk_fma_f32 v[192:193], v[220:221], v[206:207], v[192:193] neg_lo:[0,0,1] neg_hi:[0,0,1]
	v_pk_fma_f32 v[194:195], v[218:219], v[208:209], v[194:195] neg_lo:[0,0,1] neg_hi:[0,0,1]
	v_pk_mul_f32 v[150:151], v[220:221], v[198:199]
	v_pk_mul_f32 v[148:149], v[218:219], v[196:197]
	v_pk_fma_f32 v[150:151], v[224:225], v[206:207], v[150:151]
	v_pk_fma_f32 v[148:149], v[222:223], v[208:209], v[148:149]
	v_pk_mul_f32 v[192:193], s[28:29], v[192:193]
	v_pk_mul_f32 v[194:195], s[64:65], v[194:195]
	v_pk_mul_f32 v[196:197], s[28:29], v[150:151]
	v_pk_mul_f32 v[198:199], s[64:65], v[148:149]
.LBB0_211:
	v_add_u32_e32 v148, 0x90, v172
	v_mad_i64_i32 v[148:149], s[24:25], s62, v148, 0
	v_lshl_add_u64 v[148:149], v[148:149], 1, v[180:181]
	v_cvt_pk_bf16_f32 v150, v190, v191
	v_cvt_pk_bf16_f32 v151, v186, v187
	global_store_dwordx2 v[148:149], v[150:151], off nt
	v_cvt_pk_bf16_f32 v150, v188, v189
	v_cvt_pk_bf16_f32 v151, v184, v185
	global_store_dwordx2 v[148:149], v[150:151], off offset:32 nt
	v_cvt_pk_bf16_f32 v150, v194, v195
	v_cvt_pk_bf16_f32 v151, v192, v193
	global_store_dwordx2 v[148:149], v[150:151], off offset:64 nt
	v_cvt_pk_bf16_f32 v150, v198, v199
	v_cvt_pk_bf16_f32 v151, v196, v197
	global_store_dwordx2 v[148:149], v[150:151], off offset:96 nt
	s_nop 0
	s_and_b64 vcc, exec, s[40:41]
	s_nop 1
	v_fmamk_f32 v148, v216, 0x3a800000, v202
	v_rsq_f32_e32 v148, v148
	s_nop 0
	v_pk_mul_f32 v[186:187], v[34:35], v[148:149] op_sel_hi:[1,0]
	v_pk_mul_f32 v[190:191], v[32:33], v[148:149] op_sel_hi:[1,0]
	v_pk_mul_f32 v[184:185], v[30:31], v[148:149] op_sel_hi:[1,0]
	v_pk_mul_f32 v[188:189], v[28:29], v[148:149] op_sel_hi:[1,0]
	v_pk_mul_f32 v[192:193], v[26:27], v[148:149] op_sel_hi:[1,0]
	v_pk_mul_f32 v[194:195], v[24:25], v[148:149] op_sel_hi:[1,0]
	v_pk_mul_f32 v[196:197], v[22:23], v[148:149] op_sel_hi:[1,0]
	v_pk_mul_f32 v[198:199], v[20:21], v[148:149] op_sel_hi:[1,0]
	s_cbranch_vccnz .LBB0_213
	v_pk_mul_f32 v[148:149], v[186:187], v[186:187]
	v_pk_mul_f32 v[150:151], v[190:191], v[190:191]
	v_mov_b32_e32 v153, v149
	v_mov_b32_e32 v152, v150
	v_pk_mov_b32 v[148:149], v[150:151], v[148:149] op_sel:[1,0]
	v_pk_mul_f32 v[150:151], v[184:185], v[184:185]
	v_pk_add_f32 v[148:149], v[148:149], v[152:153]
	v_pk_mul_f32 v[152:153], v[188:189], v[188:189]
	v_pk_add_f32 v[148:149], v[148:149], v[148:149] op_sel_hi:[0,1]
	v_mov_b32_e32 v154, v152
	v_mov_b32_e32 v155, v151
	v_pk_mov_b32 v[150:151], v[152:153], v[150:151] op_sel:[1,0]
	v_mul_f32_e32 v148, v194, v194
	v_pk_add_f32 v[150:151], v[150:151], v[154:155]
	v_pk_fma_f32 v[152:153], v[194:195], v[194:195], v[148:149] op_sel_hi:[1,1,0]
	v_mul_f32_e32 v148, v192, v192
	v_pk_add_f32 v[150:151], v[150:151], v[150:151] op_sel_hi:[0,1]
	v_pk_fma_f32 v[154:155], v[192:193], v[192:193], v[148:149] op_sel_hi:[1,1,0]
	v_mul_f32_e32 v152, v198, v198
	v_mul_f32_e32 v154, v199, v199
	v_mul_f32_e32 v148, v196, v196
	v_mul_f32_e32 v150, v197, v197
	v_pk_add_f32 v[152:153], v[152:153], v[154:155]
	v_pk_add_f32 v[148:149], v[148:149], v[150:151]
	v_and_b32_e32 v150, 64, v204
	v_pk_add_f32 v[148:149], v[152:153], v[148:149]
	v_add_u32_e32 v150, 64, v150
	v_add_f32_e32 v148, v148, v149
	v_xor_b32_e32 v149, 16, v204
	v_cmp_lt_i32_e32 vcc, v149, v150
	v_mov_b32_e32 v183, v2
	v_lshl_add_u64 v[152:153], v[162:163], 0, v[182:183]
	v_cndmask_b32_e32 v149, v204, v149, vcc
	v_lshlrev_b32_e32 v149, 2, v149
	ds_bpermute_b32 v149, v149, v148
	global_load_dwordx4 v[152:155], v[152:153], off
	s_mov_b32 s28, s64
	s_mov_b32 s29, s64
	s_waitcnt lgkmcnt(0)
	v_add_f32_e32 v148, v148, v149
	v_xor_b32_e32 v149, 32, v204
	v_cmp_lt_i32_e32 vcc, v149, v150
	s_nop 1
	v_cndmask_b32_e32 v149, v204, v149, vcc
	v_lshlrev_b32_e32 v149, 2, v149
	ds_bpermute_b32 v149, v149, v148
	s_waitcnt lgkmcnt(0)
	v_add_f32_e32 v148, v148, v149
	v_fmamk_f32 v148, v148, 0x3c800000, v202
	v_rsq_f32_e32 v200, v148
	v_lshl_add_u64 v[148:149], v[160:161], 0, v[182:183]
	global_load_dwordx4 v[148:151], v[148:149], off
	global_load_dwordx4 v[218:221], v[164:165], off offset:2048
	global_load_dwordx4 v[222:225], v[166:167], off offset:2048
	v_pk_mul_f32 v[186:187], v[186:187], v[200:201] op_sel_hi:[1,0]
	s_nop 0
	v_pk_mul_f32 v[206:207], v[146:147], v[186:187]
	v_pk_mul_f32 v[184:185], v[184:185], v[200:201] op_sel_hi:[1,0]
	v_pk_mul_f32 v[186:187], v[188:189], v[200:201] op_sel_hi:[1,0]
	v_pk_mul_f32 v[190:191], v[190:191], v[200:201] op_sel_hi:[1,0]
	v_pk_mul_f32 v[188:189], v[140:141], v[186:187]
	v_pk_mul_f32 v[184:185], v[142:143], v[184:185]
	v_pk_mul_f32 v[208:209], v[144:145], v[190:191]
	v_pk_mul_f32 v[194:195], v[194:195], v[200:201] op_sel_hi:[1,0]
	v_pk_mul_f32 v[192:193], v[192:193], v[200:201] op_sel_hi:[1,0]
	s_waitcnt vmcnt(3)
	v_pk_mul_f32 v[186:187], v[154:155], v[184:185]
	v_pk_mul_f32 v[190:191], v[152:153], v[188:189]
	s_waitcnt vmcnt(2)
	v_pk_fma_f32 v[186:187], v[150:151], v[206:207], v[186:187] neg_lo:[0,0,1] neg_hi:[0,0,1]
	v_pk_fma_f32 v[190:191], v[148:149], v[208:209], v[190:191] neg_lo:[0,0,1] neg_hi:[0,0,1]
	v_pk_mul_f32 v[150:151], v[150:151], v[184:185]
	v_pk_mul_f32 v[148:149], v[148:149], v[188:189]
	v_pk_fma_f32 v[150:151], v[154:155], v[206:207], v[150:151]
	v_pk_fma_f32 v[148:149], v[152:153], v[208:209], v[148:149]
	v_pk_mul_f32 v[184:185], s[28:29], v[150:151]
	v_pk_mul_f32 v[188:189], s[64:65], v[148:149]
	s_nop 0
	v_pk_mul_f32 v[206:207], v[138:139], v[192:193]
	v_pk_mul_f32 v[208:209], v[136:137], v[194:195]
	v_pk_mul_f32 v[192:193], v[196:197], v[200:201] op_sel_hi:[1,0]
	v_pk_mul_f32 v[194:195], v[198:199], v[200:201] op_sel_hi:[1,0]
	v_pk_mul_f32 v[198:199], v[134:135], v[192:193]
	v_pk_mul_f32 v[196:197], v[132:133], v[194:195]
	v_pk_mul_f32 v[186:187], s[28:29], v[186:187]
	v_pk_mul_f32 v[190:191], s[64:65], v[190:191]
	s_waitcnt vmcnt(0)
	v_pk_mul_f32 v[192:193], v[224:225], v[198:199]
	v_pk_mul_f32 v[194:195], v[222:223], v[196:197]
	v_pk_fma_f32 v[192:193], v[220:221], v[206:207], v[192:193] neg_lo:[0,0,1] neg_hi:[0,0,1]
	v_pk_fma_f32 v[194:195], v[218:219], v[208:209], v[194:195] neg_lo:[0,0,1] neg_hi:[0,0,1]
	v_pk_mul_f32 v[150:151], v[220:221], v[198:199]
	v_pk_mul_f32 v[148:149], v[218:219], v[196:197]
	v_pk_fma_f32 v[150:151], v[224:225], v[206:207], v[150:151]
	v_pk_fma_f32 v[148:149], v[222:223], v[208:209], v[148:149]
	v_pk_mul_f32 v[192:193], s[28:29], v[192:193]
	v_pk_mul_f32 v[194:195], s[64:65], v[194:195]
	v_pk_mul_f32 v[196:197], s[28:29], v[150:151]
	v_pk_mul_f32 v[198:199], s[64:65], v[148:149]
.LBB0_213:
	v_add_u32_e32 v148, 0xa0, v172
	v_mad_i64_i32 v[148:149], s[24:25], s62, v148, 0
	v_lshl_add_u64 v[148:149], v[148:149], 1, v[180:181]
	v_cvt_pk_bf16_f32 v150, v190, v191
	v_cvt_pk_bf16_f32 v151, v186, v187
	global_store_dwordx2 v[148:149], v[150:151], off nt
	v_cvt_pk_bf16_f32 v150, v188, v189
	v_cvt_pk_bf16_f32 v151, v184, v185
	global_store_dwordx2 v[148:149], v[150:151], off offset:32 nt
	v_cvt_pk_bf16_f32 v150, v194, v195
	v_cvt_pk_bf16_f32 v151, v192, v193
	global_store_dwordx2 v[148:149], v[150:151], off offset:64 nt
	v_cvt_pk_bf16_f32 v150, v198, v199
	v_cvt_pk_bf16_f32 v151, v196, v197
	global_store_dwordx2 v[148:149], v[150:151], off offset:96 nt
	s_nop 0
	s_and_b64 vcc, exec, s[40:41]
	s_nop 1
	v_fmamk_f32 v148, v217, 0x3a800000, v202
	v_rsq_f32_e32 v188, v148
	s_nop 0
	v_pk_mul_f32 v[150:151], v[18:19], v[188:189] op_sel_hi:[1,0]
	v_pk_mul_f32 v[154:155], v[16:17], v[188:189] op_sel_hi:[1,0]
	v_pk_mul_f32 v[148:149], v[14:15], v[188:189] op_sel_hi:[1,0]
	v_pk_mul_f32 v[152:153], v[12:13], v[188:189] op_sel_hi:[1,0]
	v_pk_mul_f32 v[174:175], v[10:11], v[188:189] op_sel_hi:[1,0]
	v_pk_mul_f32 v[184:185], v[8:9], v[188:189] op_sel_hi:[1,0]
	v_pk_mul_f32 v[186:187], v[6:7], v[188:189] op_sel_hi:[1,0]
	v_pk_mul_f32 v[188:189], v[4:5], v[188:189] op_sel_hi:[1,0]
	s_cbranch_vccnz .LBB0_215
	v_pk_mul_f32 v[190:191], v[150:151], v[150:151]
	v_pk_mul_f32 v[192:193], v[154:155], v[154:155]
	v_mov_b32_e32 v195, v191
	v_mov_b32_e32 v194, v192
	v_pk_mov_b32 v[190:191], v[192:193], v[190:191] op_sel:[1,0]
	v_pk_mul_f32 v[192:193], v[148:149], v[148:149]
	v_pk_add_f32 v[190:191], v[190:191], v[194:195]
	v_pk_mul_f32 v[194:195], v[152:153], v[152:153]
	v_pk_add_f32 v[190:191], v[190:191], v[190:191] op_sel_hi:[0,1]
	v_mov_b32_e32 v196, v194
	v_mov_b32_e32 v197, v193
	v_pk_mov_b32 v[192:193], v[194:195], v[192:193] op_sel:[1,0]
	v_mul_f32_e32 v190, v184, v184
	v_pk_add_f32 v[192:193], v[192:193], v[196:197]
	v_pk_fma_f32 v[194:195], v[184:185], v[184:185], v[190:191] op_sel_hi:[1,1,0]
	v_mul_f32_e32 v190, v174, v174
	v_pk_add_f32 v[192:193], v[192:193], v[192:193] op_sel_hi:[0,1]
	v_pk_fma_f32 v[196:197], v[174:175], v[174:175], v[190:191] op_sel_hi:[1,1,0]
	v_mul_f32_e32 v194, v188, v188
	v_mul_f32_e32 v196, v189, v189
	v_mul_f32_e32 v190, v186, v186
	v_mul_f32_e32 v192, v187, v187
	v_pk_add_f32 v[194:195], v[194:195], v[196:197]
	v_pk_add_f32 v[190:191], v[190:191], v[192:193]
	v_xor_b32_e32 v183, 16, v204
	v_pk_add_f32 v[190:191], v[194:195], v[190:191]
	s_mov_b32 s28, s64
	v_add_f32_e32 v173, v190, v191
	v_and_b32_e32 v190, 64, v204
	v_add_u32_e32 v190, 64, v190
	v_cmp_lt_i32_e32 vcc, v183, v190
	s_mov_b32 s29, s64
	s_nop 0
	v_cndmask_b32_e32 v183, v204, v183, vcc
	v_lshlrev_b32_e32 v183, 2, v183
	ds_bpermute_b32 v183, v183, v173
	s_waitcnt lgkmcnt(0)
	v_add_f32_e32 v173, v173, v183
	v_xor_b32_e32 v183, 32, v204
	v_cmp_lt_i32_e32 vcc, v183, v190
	s_nop 1
	v_cndmask_b32_e32 v183, v204, v183, vcc
	v_lshlrev_b32_e32 v183, 2, v183
	ds_bpermute_b32 v183, v183, v173
	s_waitcnt lgkmcnt(0)
	v_add_f32_e32 v173, v173, v183
	v_mov_b32_e32 v183, v2
	v_lshl_add_u64 v[192:193], v[160:161], 0, v[182:183]
	v_lshl_add_u64 v[182:183], v[162:163], 0, v[182:183]
	global_load_dwordx4 v[192:195], v[192:193], off
	v_fmamk_f32 v173, v173, 0x3c800000, v202
	global_load_dwordx4 v[196:199], v[182:183], off
	global_load_dwordx4 v[218:221], v[164:165], off offset:3072
	global_load_dwordx4 v[222:225], v[166:167], off offset:3072
	v_rsq_f32_e32 v190, v173
	s_nop 0
	v_pk_mul_f32 v[150:151], v[150:151], v[190:191] op_sel_hi:[1,0]
	s_nop 0
	v_pk_mul_f32 v[146:147], v[146:147], v[150:151]
	v_pk_mul_f32 v[148:149], v[148:149], v[190:191] op_sel_hi:[1,0]
	v_pk_mul_f32 v[150:151], v[152:153], v[190:191] op_sel_hi:[1,0]
	v_pk_mul_f32 v[154:155], v[154:155], v[190:191] op_sel_hi:[1,0]
	v_pk_mul_f32 v[140:141], v[140:141], v[150:151]
	v_pk_mul_f32 v[142:143], v[142:143], v[148:149]
	v_pk_mul_f32 v[144:145], v[144:145], v[154:155]
	v_pk_mul_f32 v[182:183], v[184:185], v[190:191] op_sel_hi:[1,0]
	v_pk_mul_f32 v[174:175], v[174:175], v[190:191] op_sel_hi:[1,0]
	v_pk_mul_f32 v[136:137], v[136:137], v[182:183]
	v_pk_mul_f32 v[138:139], v[138:139], v[174:175]
	v_pk_mul_f32 v[174:175], v[186:187], v[190:191] op_sel_hi:[1,0]
	v_pk_mul_f32 v[182:183], v[188:189], v[190:191] op_sel_hi:[1,0]
	v_pk_mul_f32 v[134:135], v[134:135], v[174:175]
	v_pk_mul_f32 v[132:133], v[132:133], v[182:183]
	s_waitcnt vmcnt(2)
	v_pk_mul_f32 v[148:149], v[198:199], v[142:143]
	v_pk_mul_f32 v[150:151], v[196:197], v[140:141]
	v_pk_mul_f32 v[142:143], v[194:195], v[142:143]
	v_pk_mul_f32 v[140:141], v[192:193], v[140:141]
	v_pk_fma_f32 v[152:153], v[192:193], v[144:145], v[150:151] neg_lo:[0,0,1] neg_hi:[0,0,1]
	v_pk_fma_f32 v[148:149], v[194:195], v[146:147], v[148:149] neg_lo:[0,0,1] neg_hi:[0,0,1]
	v_pk_fma_f32 v[140:141], v[196:197], v[144:145], v[140:141]
	v_pk_fma_f32 v[142:143], v[198:199], v[146:147], v[142:143]
	v_pk_mul_f32 v[150:151], s[28:29], v[148:149]
	v_pk_mul_f32 v[154:155], s[64:65], v[152:153]
	v_pk_mul_f32 v[148:149], s[28:29], v[142:143]
	v_pk_mul_f32 v[152:153], s[64:65], v[140:141]
	s_nop 0
	s_waitcnt vmcnt(0)
	v_pk_mul_f32 v[174:175], v[224:225], v[134:135]
	v_pk_mul_f32 v[182:183], v[222:223], v[132:133]
	v_pk_mul_f32 v[134:135], v[220:221], v[134:135]
	v_pk_mul_f32 v[132:133], v[218:219], v[132:133]
	v_pk_fma_f32 v[182:183], v[218:219], v[136:137], v[182:183] neg_lo:[0,0,1] neg_hi:[0,0,1]
	v_pk_fma_f32 v[174:175], v[220:221], v[138:139], v[174:175] neg_lo:[0,0,1] neg_hi:[0,0,1]
	v_pk_fma_f32 v[132:133], v[222:223], v[136:137], v[132:133]
	v_pk_fma_f32 v[134:135], v[224:225], v[138:139], v[134:135]
	v_pk_mul_f32 v[174:175], s[28:29], v[174:175]
	v_pk_mul_f32 v[184:185], s[64:65], v[182:183]
	v_pk_mul_f32 v[186:187], s[28:29], v[134:135]
	v_pk_mul_f32 v[188:189], s[64:65], v[132:133]
.LBB0_215:
	v_add_u32_e32 v132, 0xb0, v172
	v_mad_i64_i32 v[132:133], s[24:25], s62, v132, 0
	v_lshl_add_u64 v[132:133], v[132:133], 1, v[180:181]
	v_cvt_pk_bf16_f32 v134, v154, v155
	v_cvt_pk_bf16_f32 v135, v150, v151
	global_store_dwordx2 v[132:133], v[134:135], off nt
	v_cvt_pk_bf16_f32 v134, v152, v153
	v_cvt_pk_bf16_f32 v135, v148, v149
	global_store_dwordx2 v[132:133], v[134:135], off offset:32 nt
	v_cvt_pk_bf16_f32 v134, v184, v185
	v_cvt_pk_bf16_f32 v135, v174, v175
	global_store_dwordx2 v[132:133], v[134:135], off offset:64 nt
	v_cvt_pk_bf16_f32 v134, v188, v189
	v_cvt_pk_bf16_f32 v135, v186, v187
	global_store_dwordx2 v[132:133], v[134:135], off offset:96 nt
	s_branch .LBB0_189
.LBB0_216:
	v_ashrrev_i32_e32 v173, 31, v172
	v_lshl_add_u64 v[132:133], v[172:173], 2, s[46:47]
	global_load_dword v210, v[132:133], off
	global_load_dword v211, v[132:133], off offset:64
	global_load_dword v212, v[132:133], off offset:128
	global_load_dword v213, v[132:133], off offset:192
	global_load_dword v214, v[132:133], off offset:512
	global_load_dword v215, v[132:133], off offset:576
	global_load_dword v216, v[132:133], off offset:640
	global_load_dword v217, v[132:133], off offset:704
	v_lshl_add_u32 v136, s95, 8, v245
	v_mov_b32_e32 v137, v2
	v_mov_b64_e32 v[134:135], s[48:49]
	v_mad_i64_i32 v[140:141], s[24:25], v172, s83, v[134:135]
	v_lshlrev_b64 v[136:137], 1, v[136:137]
	v_lshl_add_u64 v[140:141], v[140:141], 0, v[136:137]
	s_waitcnt vmcnt(7)
	s_nop 1
	v_fmamk_f32 v138, v210, 0x3a800000, v202
	v_rsq_f32_e32 v138, v138
	s_nop 0
	v_pk_mul_f32 v[130:131], v[130:131], v[138:139] op_sel_hi:[1,0]
	v_pk_mul_f32 v[128:129], v[128:129], v[138:139] op_sel_hi:[1,0]
	v_pk_mul_f32 v[126:127], v[126:127], v[138:139] op_sel_hi:[1,0]
	v_pk_mul_f32 v[124:125], v[124:125], v[138:139] op_sel_hi:[1,0]
	v_pk_mul_f32 v[122:123], v[122:123], v[138:139] op_sel_hi:[1,0]
	v_pk_mul_f32 v[120:121], v[120:121], v[138:139] op_sel_hi:[1,0]
	v_pk_mul_f32 v[142:143], v[118:119], v[138:139] op_sel_hi:[1,0]
	v_pk_mul_f32 v[138:139], v[116:117], v[138:139] op_sel_hi:[1,0]
	v_cvt_pk_bf16_f32 v116, v128, v129
	v_cvt_pk_bf16_f32 v117, v130, v131
	v_cvt_pk_bf16_f32 v118, v124, v125
	v_cvt_pk_bf16_f32 v119, v126, v127
	global_store_dwordx4 v[140:141], v[116:119], off nt
	s_nop 1
	v_cvt_pk_bf16_f32 v116, v120, v121
	v_cvt_pk_bf16_f32 v117, v122, v123
	v_cvt_pk_bf16_f32 v118, v138, v139
	v_cvt_pk_bf16_f32 v119, v142, v143
	global_store_dwordx4 v[140:141], v[116:119], off offset:256 nt
	s_nop 0
	s_nop 0
	v_or_b32_e32 v117, 16, v172
	v_mad_i64_i32 v[118:119], s[24:25], v117, s83, v[134:135]
	v_lshl_add_u64 v[118:119], v[118:119], 0, v[136:137]
	s_waitcnt vmcnt(8)
	s_nop 1
	v_fmamk_f32 v116, v211, 0x3a800000, v202
	v_rsq_f32_e32 v116, v116
	s_nop 0
	v_pk_mul_f32 v[114:115], v[114:115], v[116:117] op_sel_hi:[1,0]
	v_pk_mul_f32 v[112:113], v[112:113], v[116:117] op_sel_hi:[1,0]
	v_pk_mul_f32 v[110:111], v[110:111], v[116:117] op_sel_hi:[1,0]
	v_pk_mul_f32 v[108:109], v[108:109], v[116:117] op_sel_hi:[1,0]
	v_pk_mul_f32 v[106:107], v[106:107], v[116:117] op_sel_hi:[1,0]
	v_pk_mul_f32 v[104:105], v[104:105], v[116:117] op_sel_hi:[1,0]
	v_pk_mul_f32 v[120:121], v[102:103], v[116:117] op_sel_hi:[1,0]
	v_pk_mul_f32 v[116:117], v[100:101], v[116:117] op_sel_hi:[1,0]
	v_cvt_pk_bf16_f32 v100, v112, v113
	v_cvt_pk_bf16_f32 v101, v114, v115
	v_cvt_pk_bf16_f32 v102, v108, v109
	v_cvt_pk_bf16_f32 v103, v110, v111
	global_store_dwordx4 v[118:119], v[100:103], off nt
	s_nop 1
	v_cvt_pk_bf16_f32 v100, v104, v105
	v_cvt_pk_bf16_f32 v101, v106, v107
	v_cvt_pk_bf16_f32 v102, v116, v117
	v_cvt_pk_bf16_f32 v103, v120, v121
	global_store_dwordx4 v[118:119], v[100:103], off offset:256 nt
	s_nop 0
	s_nop 0
	v_or_b32_e32 v101, 32, v172
	v_mad_i64_i32 v[102:103], s[24:25], v101, s83, v[134:135]
	v_lshl_add_u64 v[102:103], v[102:103], 0, v[136:137]
	s_waitcnt vmcnt(9)
	s_nop 1
	v_fmamk_f32 v100, v212, 0x3a800000, v202
	v_rsq_f32_e32 v100, v100
	s_nop 0
	v_pk_mul_f32 v[98:99], v[98:99], v[100:101] op_sel_hi:[1,0]
	v_pk_mul_f32 v[96:97], v[96:97], v[100:101] op_sel_hi:[1,0]
	v_pk_mul_f32 v[94:95], v[94:95], v[100:101] op_sel_hi:[1,0]
	v_pk_mul_f32 v[92:93], v[92:93], v[100:101] op_sel_hi:[1,0]
	v_pk_mul_f32 v[90:91], v[90:91], v[100:101] op_sel_hi:[1,0]
	v_pk_mul_f32 v[88:89], v[88:89], v[100:101] op_sel_hi:[1,0]
	v_pk_mul_f32 v[104:105], v[86:87], v[100:101] op_sel_hi:[1,0]
	v_pk_mul_f32 v[100:101], v[84:85], v[100:101] op_sel_hi:[1,0]
	v_cvt_pk_bf16_f32 v84, v96, v97
	v_cvt_pk_bf16_f32 v85, v98, v99
	v_cvt_pk_bf16_f32 v86, v92, v93
	v_cvt_pk_bf16_f32 v87, v94, v95
	global_store_dwordx4 v[102:103], v[84:87], off nt
	s_nop 1
	v_cvt_pk_bf16_f32 v84, v88, v89
	v_cvt_pk_bf16_f32 v85, v90, v91
	v_cvt_pk_bf16_f32 v86, v100, v101
	v_cvt_pk_bf16_f32 v87, v104, v105
	global_store_dwordx4 v[102:103], v[84:87], off offset:256 nt
	s_nop 0
	s_nop 0
	v_or_b32_e32 v85, 48, v172
	v_mad_i64_i32 v[86:87], s[24:25], v85, s83, v[134:135]
	v_lshl_add_u64 v[86:87], v[86:87], 0, v[136:137]
	s_waitcnt vmcnt(10)
	s_nop 1
	v_fmamk_f32 v84, v213, 0x3a800000, v202
	v_rsq_f32_e32 v84, v84
	s_nop 0
	v_pk_mul_f32 v[82:83], v[82:83], v[84:85] op_sel_hi:[1,0]
	v_pk_mul_f32 v[80:81], v[80:81], v[84:85] op_sel_hi:[1,0]
	v_pk_mul_f32 v[78:79], v[78:79], v[84:85] op_sel_hi:[1,0]
	v_pk_mul_f32 v[76:77], v[76:77], v[84:85] op_sel_hi:[1,0]
	v_pk_mul_f32 v[74:75], v[74:75], v[84:85] op_sel_hi:[1,0]
	v_pk_mul_f32 v[72:73], v[72:73], v[84:85] op_sel_hi:[1,0]
	v_pk_mul_f32 v[88:89], v[70:71], v[84:85] op_sel_hi:[1,0]
	v_pk_mul_f32 v[84:85], v[68:69], v[84:85] op_sel_hi:[1,0]
	v_cvt_pk_bf16_f32 v68, v80, v81
	v_cvt_pk_bf16_f32 v69, v82, v83
	v_cvt_pk_bf16_f32 v70, v76, v77
	v_cvt_pk_bf16_f32 v71, v78, v79
	global_store_dwordx4 v[86:87], v[68:71], off nt
	s_nop 1
	v_cvt_pk_bf16_f32 v68, v72, v73
	v_cvt_pk_bf16_f32 v69, v74, v75
	v_cvt_pk_bf16_f32 v70, v84, v85
	v_cvt_pk_bf16_f32 v71, v88, v89
	global_store_dwordx4 v[86:87], v[68:71], off offset:256 nt
	s_nop 0
	s_nop 0
	v_add_u32_e32 v69, 0x80, v172
	v_mad_i64_i32 v[70:71], s[24:25], v69, s83, v[134:135]
	v_lshl_add_u64 v[70:71], v[70:71], 0, v[136:137]
	s_waitcnt vmcnt(11)
	s_nop 1
	v_fmamk_f32 v68, v214, 0x3a800000, v202
	v_rsq_f32_e32 v68, v68
	s_nop 0
	v_pk_mul_f32 v[66:67], v[66:67], v[68:69] op_sel_hi:[1,0]
	v_pk_mul_f32 v[64:65], v[64:65], v[68:69] op_sel_hi:[1,0]
	v_pk_mul_f32 v[62:63], v[62:63], v[68:69] op_sel_hi:[1,0]
	v_pk_mul_f32 v[60:61], v[60:61], v[68:69] op_sel_hi:[1,0]
	v_pk_mul_f32 v[58:59], v[58:59], v[68:69] op_sel_hi:[1,0]
	v_pk_mul_f32 v[56:57], v[56:57], v[68:69] op_sel_hi:[1,0]
	v_pk_mul_f32 v[72:73], v[54:55], v[68:69] op_sel_hi:[1,0]
	v_pk_mul_f32 v[68:69], v[52:53], v[68:69] op_sel_hi:[1,0]
	v_cvt_pk_bf16_f32 v52, v64, v65
	v_cvt_pk_bf16_f32 v53, v66, v67
	v_cvt_pk_bf16_f32 v54, v60, v61
	v_cvt_pk_bf16_f32 v55, v62, v63
	global_store_dwordx4 v[70:71], v[52:55], off nt
	s_nop 1
	v_cvt_pk_bf16_f32 v52, v56, v57
	v_cvt_pk_bf16_f32 v53, v58, v59
	v_cvt_pk_bf16_f32 v54, v68, v69
	v_cvt_pk_bf16_f32 v55, v72, v73
	global_store_dwordx4 v[70:71], v[52:55], off offset:256 nt
	s_nop 0
	s_nop 0
	v_add_u32_e32 v53, 0x90, v172
	v_mad_i64_i32 v[54:55], s[24:25], v53, s83, v[134:135]
	v_lshl_add_u64 v[54:55], v[54:55], 0, v[136:137]
	s_waitcnt vmcnt(12)
	s_nop 1
	v_fmamk_f32 v52, v215, 0x3a800000, v202
	v_rsq_f32_e32 v52, v52
	s_nop 0
	v_pk_mul_f32 v[50:51], v[50:51], v[52:53] op_sel_hi:[1,0]
	v_pk_mul_f32 v[48:49], v[48:49], v[52:53] op_sel_hi:[1,0]
	v_pk_mul_f32 v[46:47], v[46:47], v[52:53] op_sel_hi:[1,0]
	v_pk_mul_f32 v[44:45], v[44:45], v[52:53] op_sel_hi:[1,0]
	v_pk_mul_f32 v[42:43], v[42:43], v[52:53] op_sel_hi:[1,0]
	v_pk_mul_f32 v[40:41], v[40:41], v[52:53] op_sel_hi:[1,0]
	v_pk_mul_f32 v[56:57], v[38:39], v[52:53] op_sel_hi:[1,0]
	v_pk_mul_f32 v[52:53], v[36:37], v[52:53] op_sel_hi:[1,0]
	v_cvt_pk_bf16_f32 v36, v48, v49
	v_cvt_pk_bf16_f32 v37, v50, v51
	v_cvt_pk_bf16_f32 v38, v44, v45
	v_cvt_pk_bf16_f32 v39, v46, v47
	global_store_dwordx4 v[54:55], v[36:39], off nt
	s_nop 1
	v_cvt_pk_bf16_f32 v36, v40, v41
	v_cvt_pk_bf16_f32 v37, v42, v43
	v_cvt_pk_bf16_f32 v38, v52, v53
	v_cvt_pk_bf16_f32 v39, v56, v57
	global_store_dwordx4 v[54:55], v[36:39], off offset:256 nt
	s_nop 0
	s_nop 0
	v_add_u32_e32 v37, 0xa0, v172
	v_mad_i64_i32 v[38:39], s[24:25], v37, s83, v[134:135]
	v_lshl_add_u64 v[38:39], v[38:39], 0, v[136:137]
	s_waitcnt vmcnt(13)
	s_nop 1
	v_fmamk_f32 v36, v216, 0x3a800000, v202
	v_rsq_f32_e32 v36, v36
	s_nop 0
	v_pk_mul_f32 v[34:35], v[34:35], v[36:37] op_sel_hi:[1,0]
	v_pk_mul_f32 v[32:33], v[32:33], v[36:37] op_sel_hi:[1,0]
	v_pk_mul_f32 v[30:31], v[30:31], v[36:37] op_sel_hi:[1,0]
	v_pk_mul_f32 v[28:29], v[28:29], v[36:37] op_sel_hi:[1,0]
	v_pk_mul_f32 v[26:27], v[26:27], v[36:37] op_sel_hi:[1,0]
	v_pk_mul_f32 v[24:25], v[24:25], v[36:37] op_sel_hi:[1,0]
	v_pk_mul_f32 v[40:41], v[22:23], v[36:37] op_sel_hi:[1,0]
	v_pk_mul_f32 v[36:37], v[20:21], v[36:37] op_sel_hi:[1,0]
	v_cvt_pk_bf16_f32 v20, v32, v33
	v_cvt_pk_bf16_f32 v21, v34, v35
	v_cvt_pk_bf16_f32 v22, v28, v29
	v_cvt_pk_bf16_f32 v23, v30, v31
	global_store_dwordx4 v[38:39], v[20:23], off nt
	s_nop 1
	v_cvt_pk_bf16_f32 v20, v24, v25
	v_cvt_pk_bf16_f32 v21, v26, v27
	v_cvt_pk_bf16_f32 v22, v36, v37
	v_cvt_pk_bf16_f32 v23, v40, v41
	global_store_dwordx4 v[38:39], v[20:23], off offset:256 nt
	s_nop 0
	s_nop 0
	v_add_u32_e32 v21, 0xb0, v172
	v_mad_i64_i32 v[22:23], s[24:25], v21, s83, v[134:135]
	v_lshl_add_u64 v[22:23], v[22:23], 0, v[136:137]
	s_waitcnt vmcnt(14)
	s_nop 1
	v_fmamk_f32 v20, v217, 0x3a800000, v202
	v_rsq_f32_e32 v20, v20
	s_nop 0
	v_pk_mul_f32 v[18:19], v[18:19], v[20:21] op_sel_hi:[1,0]
	v_pk_mul_f32 v[16:17], v[16:17], v[20:21] op_sel_hi:[1,0]
	v_pk_mul_f32 v[14:15], v[14:15], v[20:21] op_sel_hi:[1,0]
	v_pk_mul_f32 v[12:13], v[12:13], v[20:21] op_sel_hi:[1,0]
	v_pk_mul_f32 v[10:11], v[10:11], v[20:21] op_sel_hi:[1,0]
	v_pk_mul_f32 v[8:9], v[8:9], v[20:21] op_sel_hi:[1,0]
	v_pk_mul_f32 v[24:25], v[6:7], v[20:21] op_sel_hi:[1,0]
	v_pk_mul_f32 v[20:21], v[4:5], v[20:21] op_sel_hi:[1,0]
	v_cvt_pk_bf16_f32 v4, v16, v17
	v_cvt_pk_bf16_f32 v5, v18, v19
	v_cvt_pk_bf16_f32 v6, v12, v13
	v_cvt_pk_bf16_f32 v7, v14, v15
	global_store_dwordx4 v[22:23], v[4:7], off nt
	s_nop 1
	v_cvt_pk_bf16_f32 v4, v8, v9
	v_cvt_pk_bf16_f32 v5, v10, v11
	v_cvt_pk_bf16_f32 v6, v20, v21
	v_cvt_pk_bf16_f32 v7, v24, v25
	global_store_dwordx4 v[22:23], v[4:7], off offset:256 nt
	s_andn2_b64 vcc, exec, s[38:39]
	s_mov_b64 s[24:25], -1
	s_cbranch_vccnz .LBB0_180

.LBB0_803:
	v_lshl_add_u32 v140, s91, 8, v3
	v_lshl_or_b32 v138, s90, 8, v143
	v_ashrrev_i32_e32 v141, 31, v140
	v_ashrrev_i32_e32 v139, 31, v138
	v_lshlrev_b64 v[146:147], 10, v[140:141]
	v_lshl_add_u64 v[154:155], v[146:147], 0, v[138:139]
	v_lshlrev_b64 v[156:157], 2, v[154:155]
	v_lshl_add_u64 v[158:159], s[28:29], 0, v[156:157]
	global_load_dwordx4 v[146:149], v[158:159], off
	global_load_dwordx4 v[150:153], v[158:159], off offset:16
	v_lshl_add_u64 v[160:161], v[154:155], 1, s[50:51]
	v_lshl_add_u64 v[162:163], s[44:45], 0, v[156:157]
	v_xor_b32_e32 v145, 32, v204
	s_waitcnt vmcnt(0)
	v_pk_add_f32 v[130:131], v[130:131], v[148:149]
	v_pk_add_f32 v[128:129], v[128:129], v[146:147]
	v_pk_add_f32 v[148:149], v[126:127], v[152:153]
	v_pk_add_f32 v[146:147], v[124:125], v[150:151]
	global_store_dwordx4 v[162:163], v[128:131], off nt
	global_store_dwordx4 v[162:163], v[146:149], off offset:16 nt
	v_cvt_pk_bf16_f32 v124, v128, v129
	v_cvt_pk_bf16_f32 v125, v130, v131
	v_cvt_pk_bf16_f32 v126, v146, v147
	v_cvt_pk_bf16_f32 v127, v148, v149
	global_store_dwordx4 v[160:161], v[124:127], off nt
	global_load_dwordx4 v[150:153], v[158:159], off offset:512
	global_load_dwordx4 v[154:157], v[158:159], off offset:528
	v_mul_f32_e32 v126, v129, v129
	v_mul_f32_e32 v127, v131, v131
	v_mul_f32_e32 v129, v147, v147
	v_mul_f32_e32 v131, v149, v149
	v_fmac_f32_e32 v126, v128, v128
	v_fmac_f32_e32 v127, v130, v130
	v_fmac_f32_e32 v129, v146, v146
	v_fmac_f32_e32 v131, v148, v148
	v_add_f32_e32 v126, v126, v127
	v_add_f32_e32 v127, v129, v131
	v_add_f32_e32 v130, v126, v127
	v_and_b32_e32 v125, 64, v204
	v_xor_b32_e32 v124, 16, v204
	v_add_u32_e32 v125, 64, v125
	v_cmp_lt_i32_e32 vcc, v124, v125
	s_waitcnt vmcnt(1)
	v_pk_add_f32 v[122:123], v[122:123], v[152:153]
	v_pk_add_f32 v[120:121], v[120:121], v[150:151]
	s_waitcnt vmcnt(0)
	v_pk_add_f32 v[128:129], v[118:119], v[156:157]
	v_pk_add_f32 v[126:127], v[116:117], v[154:155]
	v_mul_f32_e32 v116, v121, v121
	v_mul_f32_e32 v117, v123, v123
	v_mul_f32_e32 v118, v127, v127
	v_mul_f32_e32 v119, v129, v129
	v_fmac_f32_e32 v116, v120, v120
	v_fmac_f32_e32 v117, v122, v122
	v_fmac_f32_e32 v118, v126, v126
	v_fmac_f32_e32 v119, v128, v128
	v_add_f32_e32 v116, v116, v117
	v_add_f32_e32 v117, v118, v119
	v_cndmask_b32_e32 v124, v204, v124, vcc
	v_add_f32_e32 v116, v116, v117
	v_lshlrev_b32_e32 v124, 2, v124
	v_add_f32_e32 v116, v130, v116
	ds_bpermute_b32 v117, v124, v116
	v_cmp_lt_i32_e32 vcc, v145, v125
	global_store_dwordx4 v[162:163], v[120:123], off offset:512 nt
	global_store_dwordx4 v[162:163], v[126:129], off offset:528 nt
	v_cndmask_b32_e32 v118, v204, v145, vcc
	v_lshlrev_b32_e32 v118, 2, v118
	s_waitcnt lgkmcnt(0)
	v_add_f32_e32 v116, v116, v117
	ds_bpermute_b32 v117, v118, v116
	v_cvt_pk_bf16_f32 v120, v120, v121
	v_cvt_pk_bf16_f32 v121, v122, v123
	v_cvt_pk_bf16_f32 v122, v126, v127
	v_cvt_pk_bf16_f32 v123, v128, v129
	global_store_dwordx4 v[160:161], v[120:123], off offset:256 nt
	s_and_saveexec_b64 s[24:25], s[40:41]
	s_cbranch_execz .LBB0_805
	v_lshl_add_u64 v[120:121], v[140:141], 2, s[46:47]
	s_waitcnt lgkmcnt(0)
	v_add_f32_e32 v116, v116, v117
	global_atomic_add_f32 v[120:121], v116, off
.LBB0_805:
	s_or_b64 exec, exec, s[24:25]
	v_or_b32_e32 v116, 16, v140
	s_waitcnt lgkmcnt(0)
	v_ashrrev_i32_e32 v117, 31, v116
	v_lshlrev_b64 v[120:121], 10, v[116:117]
	v_lshl_add_u64 v[130:131], v[120:121], 0, v[138:139]
	v_lshlrev_b64 v[146:147], 2, v[130:131]
	v_lshl_add_u64 v[148:149], s[28:29], 0, v[146:147]
	global_load_dwordx4 v[120:123], v[148:149], off
	global_load_dwordx4 v[126:129], v[148:149], off offset:16
	v_lshl_add_u64 v[130:131], v[130:131], 1, s[50:51]
	v_lshl_add_u64 v[146:147], s[44:45], 0, v[146:147]
	s_waitcnt vmcnt(1)
	v_pk_add_f32 v[114:115], v[114:115], v[122:123]
	v_pk_add_f32 v[112:113], v[112:113], v[120:121]
	s_waitcnt vmcnt(0)
	v_pk_add_f32 v[110:111], v[110:111], v[128:129]
	v_pk_add_f32 v[108:109], v[108:109], v[126:127]
	global_store_dwordx4 v[146:147], v[112:115], off nt
	global_store_dwordx4 v[146:147], v[108:111], off offset:16 nt
	v_cvt_pk_bf16_f32 v120, v112, v113
	v_cvt_pk_bf16_f32 v121, v114, v115
	v_cvt_pk_bf16_f32 v122, v108, v109
	v_cvt_pk_bf16_f32 v123, v110, v111
	global_store_dwordx4 v[130:131], v[120:123], off nt
	global_load_dwordx4 v[120:123], v[148:149], off offset:512
	s_nop 0
	global_load_dwordx4 v[126:129], v[148:149], off offset:528
	v_mul_f32_e32 v113, v113, v113
	v_mul_f32_e32 v115, v115, v115
	v_mul_f32_e32 v109, v109, v109
	v_mul_f32_e32 v111, v111, v111
	v_fmac_f32_e32 v113, v112, v112
	v_fmac_f32_e32 v115, v114, v114
	v_fmac_f32_e32 v109, v108, v108
	v_fmac_f32_e32 v111, v110, v110
	v_add_f32_e32 v108, v113, v115
	v_add_f32_e32 v109, v109, v111
	v_add_f32_e32 v112, v108, v109
	s_waitcnt vmcnt(1)
	v_pk_add_f32 v[106:107], v[106:107], v[122:123]
	v_pk_add_f32 v[104:105], v[104:105], v[120:121]
	s_waitcnt vmcnt(0)
	v_pk_add_f32 v[110:111], v[102:103], v[128:129]
	v_pk_add_f32 v[108:109], v[100:101], v[126:127]
	v_mul_f32_e32 v100, v105, v105
	v_mul_f32_e32 v101, v107, v107
	v_mul_f32_e32 v102, v109, v109
	v_mul_f32_e32 v103, v111, v111
	v_fmac_f32_e32 v100, v104, v104
	v_fmac_f32_e32 v101, v106, v106
	v_fmac_f32_e32 v102, v108, v108
	v_fmac_f32_e32 v103, v110, v110
	v_add_f32_e32 v100, v100, v101
	v_add_f32_e32 v101, v102, v103
	v_add_f32_e32 v100, v100, v101
	v_add_f32_e32 v100, v112, v100
	ds_bpermute_b32 v101, v124, v100
	global_store_dwordx4 v[146:147], v[104:107], off offset:512 nt
	global_store_dwordx4 v[146:147], v[108:111], off offset:528 nt
	v_cvt_pk_bf16_f32 v102, v104, v105
	v_cvt_pk_bf16_f32 v103, v106, v107
	s_waitcnt lgkmcnt(0)
	v_add_f32_e32 v100, v100, v101
	ds_bpermute_b32 v101, v118, v100
	v_cvt_pk_bf16_f32 v104, v108, v109
	v_cvt_pk_bf16_f32 v105, v110, v111
	global_store_dwordx4 v[130:131], v[102:105], off offset:256 nt
	s_and_saveexec_b64 s[24:25], s[40:41]
	s_cbranch_execz .LBB0_807
	v_lshl_add_u64 v[102:103], v[116:117], 2, s[46:47]
	s_waitcnt lgkmcnt(0)
	v_add_f32_e32 v100, v100, v101
	global_atomic_add_f32 v[102:103], v100, off
.LBB0_807:
	s_or_b64 exec, exec, s[24:25]
	v_or_b32_e32 v100, 32, v140
	s_waitcnt lgkmcnt(0)
	v_ashrrev_i32_e32 v101, 31, v100
	v_lshlrev_b64 v[102:103], 10, v[100:101]
	v_lshl_add_u64 v[110:111], v[102:103], 0, v[138:139]
	v_lshlrev_b64 v[112:113], 2, v[110:111]
	v_lshl_add_u64 v[114:115], s[28:29], 0, v[112:113]
	global_load_dwordx4 v[102:105], v[114:115], off
	global_load_dwordx4 v[106:109], v[114:115], off offset:16
	v_lshl_add_u64 v[110:111], v[110:111], 1, s[50:51]
	v_lshl_add_u64 v[112:113], s[44:45], 0, v[112:113]
	s_waitcnt vmcnt(1)
	v_pk_add_f32 v[98:99], v[98:99], v[104:105]
	v_pk_add_f32 v[96:97], v[96:97], v[102:103]
	s_waitcnt vmcnt(0)
	v_pk_add_f32 v[94:95], v[94:95], v[108:109]
	v_pk_add_f32 v[92:93], v[92:93], v[106:107]
	global_store_dwordx4 v[112:113], v[96:99], off nt
	global_store_dwordx4 v[112:113], v[92:95], off offset:16 nt
	v_cvt_pk_bf16_f32 v102, v96, v97
	v_cvt_pk_bf16_f32 v103, v98, v99
	v_cvt_pk_bf16_f32 v104, v92, v93
	v_cvt_pk_bf16_f32 v105, v94, v95
	global_store_dwordx4 v[110:111], v[102:105], off nt
	global_load_dwordx4 v[102:105], v[114:115], off offset:512
	s_nop 0
	global_load_dwordx4 v[106:109], v[114:115], off offset:528
	v_mul_f32_e32 v97, v97, v97
	v_mul_f32_e32 v99, v99, v99
	v_mul_f32_e32 v93, v93, v93
	v_mul_f32_e32 v95, v95, v95
	v_fmac_f32_e32 v97, v96, v96
	v_fmac_f32_e32 v99, v98, v98
	v_fmac_f32_e32 v93, v92, v92
	v_fmac_f32_e32 v95, v94, v94
	v_add_f32_e32 v92, v97, v99
	v_add_f32_e32 v93, v93, v95
	v_add_f32_e32 v96, v92, v93
	s_waitcnt vmcnt(1)
	v_pk_add_f32 v[90:91], v[90:91], v[104:105]
	v_pk_add_f32 v[88:89], v[88:89], v[102:103]
	s_waitcnt vmcnt(0)
	v_pk_add_f32 v[94:95], v[86:87], v[108:109]
	v_pk_add_f32 v[92:93], v[84:85], v[106:107]
	v_mul_f32_e32 v84, v89, v89
	v_mul_f32_e32 v85, v91, v91
	v_mul_f32_e32 v86, v93, v93
	v_mul_f32_e32 v87, v95, v95
	v_fmac_f32_e32 v84, v88, v88
	v_fmac_f32_e32 v85, v90, v90
	v_fmac_f32_e32 v86, v92, v92
	v_fmac_f32_e32 v87, v94, v94
	v_add_f32_e32 v84, v84, v85
	v_add_f32_e32 v85, v86, v87
	v_add_f32_e32 v84, v84, v85
	v_add_f32_e32 v84, v96, v84
	ds_bpermute_b32 v85, v124, v84
	global_store_dwordx4 v[112:113], v[88:91], off offset:512 nt
	global_store_dwordx4 v[112:113], v[92:95], off offset:528 nt
	v_cvt_pk_bf16_f32 v86, v88, v89
	v_cvt_pk_bf16_f32 v87, v90, v91
	s_waitcnt lgkmcnt(0)
	v_add_f32_e32 v84, v84, v85
	ds_bpermute_b32 v85, v118, v84
	v_cvt_pk_bf16_f32 v88, v92, v93
	v_cvt_pk_bf16_f32 v89, v94, v95
	global_store_dwordx4 v[110:111], v[86:89], off offset:256 nt
	s_and_saveexec_b64 s[24:25], s[40:41]
	s_cbranch_execz .LBB0_809
	v_lshl_add_u64 v[86:87], v[100:101], 2, s[46:47]
	s_waitcnt lgkmcnt(0)
	v_add_f32_e32 v84, v84, v85
	global_atomic_add_f32 v[86:87], v84, off
.LBB0_809:
	s_or_b64 exec, exec, s[24:25]
	v_or_b32_e32 v84, 48, v140
	s_waitcnt lgkmcnt(0)
	v_ashrrev_i32_e32 v85, 31, v84
	v_lshlrev_b64 v[86:87], 10, v[84:85]
	v_lshl_add_u64 v[94:95], v[86:87], 0, v[138:139]
	v_lshlrev_b64 v[96:97], 2, v[94:95]
	v_lshl_add_u64 v[98:99], s[28:29], 0, v[96:97]
	global_load_dwordx4 v[86:89], v[98:99], off
	global_load_dwordx4 v[90:93], v[98:99], off offset:16
	v_lshl_add_u64 v[94:95], v[94:95], 1, s[50:51]
	v_lshl_add_u64 v[96:97], s[44:45], 0, v[96:97]
	s_waitcnt vmcnt(1)
	v_pk_add_f32 v[82:83], v[82:83], v[88:89]
	v_pk_add_f32 v[80:81], v[80:81], v[86:87]
	s_waitcnt vmcnt(0)
	v_pk_add_f32 v[78:79], v[78:79], v[92:93]
	v_pk_add_f32 v[76:77], v[76:77], v[90:91]
	global_store_dwordx4 v[96:97], v[80:83], off nt
	global_store_dwordx4 v[96:97], v[76:79], off offset:16 nt
	v_cvt_pk_bf16_f32 v86, v80, v81
	v_cvt_pk_bf16_f32 v87, v82, v83
	v_cvt_pk_bf16_f32 v88, v76, v77
	v_cvt_pk_bf16_f32 v89, v78, v79
	global_store_dwordx4 v[94:95], v[86:89], off nt
	global_load_dwordx4 v[86:89], v[98:99], off offset:512
	s_nop 0
	global_load_dwordx4 v[90:93], v[98:99], off offset:528
	v_mul_f32_e32 v81, v81, v81
	v_mul_f32_e32 v83, v83, v83
	v_mul_f32_e32 v77, v77, v77
	v_mul_f32_e32 v79, v79, v79
	v_fmac_f32_e32 v81, v80, v80
	v_fmac_f32_e32 v83, v82, v82
	v_fmac_f32_e32 v77, v76, v76
	v_fmac_f32_e32 v79, v78, v78
	v_add_f32_e32 v76, v81, v83
	v_add_f32_e32 v77, v77, v79
	v_add_f32_e32 v80, v76, v77
	s_waitcnt vmcnt(1)
	v_pk_add_f32 v[74:75], v[74:75], v[88:89]
	v_pk_add_f32 v[72:73], v[72:73], v[86:87]
	s_waitcnt vmcnt(0)
	v_pk_add_f32 v[78:79], v[70:71], v[92:93]
	v_pk_add_f32 v[76:77], v[68:69], v[90:91]
	v_mul_f32_e32 v68, v73, v73
	v_mul_f32_e32 v69, v75, v75
	v_mul_f32_e32 v70, v77, v77
	v_mul_f32_e32 v71, v79, v79
	v_fmac_f32_e32 v68, v72, v72
	v_fmac_f32_e32 v69, v74, v74
	v_fmac_f32_e32 v70, v76, v76
	v_fmac_f32_e32 v71, v78, v78
	v_add_f32_e32 v68, v68, v69
	v_add_f32_e32 v69, v70, v71
	v_add_f32_e32 v68, v68, v69
	v_add_f32_e32 v68, v80, v68
	ds_bpermute_b32 v69, v124, v68
	global_store_dwordx4 v[96:97], v[72:75], off offset:512 nt
	global_store_dwordx4 v[96:97], v[76:79], off offset:528 nt
	v_cvt_pk_bf16_f32 v70, v72, v73
	v_cvt_pk_bf16_f32 v71, v74, v75
	s_waitcnt lgkmcnt(0)
	v_add_f32_e32 v68, v68, v69
	ds_bpermute_b32 v69, v118, v68
	v_cvt_pk_bf16_f32 v72, v76, v77
	v_cvt_pk_bf16_f32 v73, v78, v79
	global_store_dwordx4 v[94:95], v[70:73], off offset:256 nt
	s_and_saveexec_b64 s[24:25], s[40:41]
	s_cbranch_execz .LBB0_811
	v_lshl_add_u64 v[70:71], v[84:85], 2, s[46:47]
	s_waitcnt lgkmcnt(0)
	v_add_f32_e32 v68, v68, v69
	global_atomic_add_f32 v[70:71], v68, off
.LBB0_811:
	s_or_b64 exec, exec, s[24:25]
	v_add_u32_e32 v68, 0x80, v140
	s_waitcnt lgkmcnt(0)
	v_ashrrev_i32_e32 v69, 31, v68
	v_lshlrev_b64 v[70:71], 10, v[68:69]
	v_lshl_add_u64 v[78:79], v[70:71], 0, v[138:139]
	v_lshlrev_b64 v[80:81], 2, v[78:79]
	v_lshl_add_u64 v[82:83], s[28:29], 0, v[80:81]
	global_load_dwordx4 v[70:73], v[82:83], off
	global_load_dwordx4 v[74:77], v[82:83], off offset:16
	v_lshl_add_u64 v[78:79], v[78:79], 1, s[50:51]
	v_lshl_add_u64 v[80:81], s[44:45], 0, v[80:81]
	s_waitcnt vmcnt(1)
	v_pk_add_f32 v[66:67], v[66:67], v[72:73]
	v_pk_add_f32 v[64:65], v[64:65], v[70:71]
	s_waitcnt vmcnt(0)
	v_pk_add_f32 v[62:63], v[62:63], v[76:77]
	v_pk_add_f32 v[60:61], v[60:61], v[74:75]
	global_store_dwordx4 v[80:81], v[64:67], off nt
	global_store_dwordx4 v[80:81], v[60:63], off offset:16 nt
	v_cvt_pk_bf16_f32 v70, v64, v65
	v_cvt_pk_bf16_f32 v71, v66, v67
	v_cvt_pk_bf16_f32 v72, v60, v61
	v_cvt_pk_bf16_f32 v73, v62, v63
	global_store_dwordx4 v[78:79], v[70:73], off nt
	global_load_dwordx4 v[70:73], v[82:83], off offset:512
	s_nop 0
	global_load_dwordx4 v[74:77], v[82:83], off offset:528
	v_mul_f32_e32 v65, v65, v65
	v_mul_f32_e32 v67, v67, v67
	v_mul_f32_e32 v61, v61, v61
	v_mul_f32_e32 v63, v63, v63
	v_fmac_f32_e32 v65, v64, v64
	v_fmac_f32_e32 v67, v66, v66
	v_fmac_f32_e32 v61, v60, v60
	v_fmac_f32_e32 v63, v62, v62
	v_add_f32_e32 v60, v65, v67
	v_add_f32_e32 v61, v61, v63
	v_add_f32_e32 v64, v60, v61
	s_waitcnt vmcnt(1)
	v_pk_add_f32 v[58:59], v[58:59], v[72:73]
	v_pk_add_f32 v[56:57], v[56:57], v[70:71]
	s_waitcnt vmcnt(0)
	v_pk_add_f32 v[62:63], v[54:55], v[76:77]
	v_pk_add_f32 v[60:61], v[52:53], v[74:75]
	v_mul_f32_e32 v52, v57, v57
	v_mul_f32_e32 v53, v59, v59
	v_mul_f32_e32 v54, v61, v61
	v_mul_f32_e32 v55, v63, v63
	v_fmac_f32_e32 v52, v56, v56
	v_fmac_f32_e32 v53, v58, v58
	v_fmac_f32_e32 v54, v60, v60
	v_fmac_f32_e32 v55, v62, v62
	v_add_f32_e32 v52, v52, v53
	v_add_f32_e32 v53, v54, v55
	v_add_f32_e32 v52, v52, v53
	v_add_f32_e32 v52, v64, v52
	ds_bpermute_b32 v53, v124, v52
	global_store_dwordx4 v[80:81], v[56:59], off offset:512 nt
	global_store_dwordx4 v[80:81], v[60:63], off offset:528 nt
	v_cvt_pk_bf16_f32 v54, v56, v57
	v_cvt_pk_bf16_f32 v55, v58, v59
	s_waitcnt lgkmcnt(0)
	v_add_f32_e32 v52, v52, v53
	ds_bpermute_b32 v53, v118, v52
	v_cvt_pk_bf16_f32 v56, v60, v61
	v_cvt_pk_bf16_f32 v57, v62, v63
	global_store_dwordx4 v[78:79], v[54:57], off offset:256 nt
	s_and_saveexec_b64 s[24:25], s[40:41]
	s_cbranch_execz .LBB0_813
	v_lshl_add_u64 v[54:55], v[68:69], 2, s[46:47]
	s_waitcnt lgkmcnt(0)
	v_add_f32_e32 v52, v52, v53
	global_atomic_add_f32 v[54:55], v52, off
.LBB0_813:
	s_or_b64 exec, exec, s[24:25]
	v_add_u32_e32 v52, 0x90, v140
	s_waitcnt lgkmcnt(0)
	v_ashrrev_i32_e32 v53, 31, v52
	v_lshlrev_b64 v[54:55], 10, v[52:53]
	v_lshl_add_u64 v[62:63], v[54:55], 0, v[138:139]
	v_lshlrev_b64 v[64:65], 2, v[62:63]
	v_lshl_add_u64 v[66:67], s[28:29], 0, v[64:65]
	global_load_dwordx4 v[54:57], v[66:67], off
	global_load_dwordx4 v[58:61], v[66:67], off offset:16
	v_lshl_add_u64 v[62:63], v[62:63], 1, s[50:51]
	v_lshl_add_u64 v[64:65], s[44:45], 0, v[64:65]
	s_waitcnt vmcnt(1)
	v_pk_add_f32 v[50:51], v[50:51], v[56:57]
	v_pk_add_f32 v[48:49], v[48:49], v[54:55]
	s_waitcnt vmcnt(0)
	v_pk_add_f32 v[46:47], v[46:47], v[60:61]
	v_pk_add_f32 v[44:45], v[44:45], v[58:59]
	global_store_dwordx4 v[64:65], v[48:51], off nt
	global_store_dwordx4 v[64:65], v[44:47], off offset:16 nt
	v_cvt_pk_bf16_f32 v54, v48, v49
	v_cvt_pk_bf16_f32 v55, v50, v51
	v_cvt_pk_bf16_f32 v56, v44, v45
	v_cvt_pk_bf16_f32 v57, v46, v47
	global_store_dwordx4 v[62:63], v[54:57], off nt
	global_load_dwordx4 v[54:57], v[66:67], off offset:512
	s_nop 0
	global_load_dwordx4 v[58:61], v[66:67], off offset:528
	v_mul_f32_e32 v49, v49, v49
	v_mul_f32_e32 v51, v51, v51
	v_mul_f32_e32 v45, v45, v45
	v_mul_f32_e32 v47, v47, v47
	v_fmac_f32_e32 v49, v48, v48
	v_fmac_f32_e32 v51, v50, v50
	v_fmac_f32_e32 v45, v44, v44
	v_fmac_f32_e32 v47, v46, v46
	v_add_f32_e32 v44, v49, v51
	v_add_f32_e32 v45, v45, v47
	v_add_f32_e32 v48, v44, v45
	s_waitcnt vmcnt(1)
	v_pk_add_f32 v[42:43], v[42:43], v[56:57]
	v_pk_add_f32 v[40:41], v[40:41], v[54:55]
	s_waitcnt vmcnt(0)
	v_pk_add_f32 v[46:47], v[38:39], v[60:61]
	v_pk_add_f32 v[44:45], v[36:37], v[58:59]
	v_mul_f32_e32 v36, v41, v41
	v_mul_f32_e32 v37, v43, v43
	v_mul_f32_e32 v38, v45, v45
	v_mul_f32_e32 v39, v47, v47
	v_fmac_f32_e32 v36, v40, v40
	v_fmac_f32_e32 v37, v42, v42
	v_fmac_f32_e32 v38, v44, v44
	v_fmac_f32_e32 v39, v46, v46
	v_add_f32_e32 v36, v36, v37
	v_add_f32_e32 v37, v38, v39
	v_add_f32_e32 v36, v36, v37
	v_add_f32_e32 v36, v48, v36
	ds_bpermute_b32 v37, v124, v36
	global_store_dwordx4 v[64:65], v[40:43], off offset:512 nt
	global_store_dwordx4 v[64:65], v[44:47], off offset:528 nt
	v_cvt_pk_bf16_f32 v38, v40, v41
	v_cvt_pk_bf16_f32 v39, v42, v43
	s_waitcnt lgkmcnt(0)
	v_add_f32_e32 v36, v36, v37
	ds_bpermute_b32 v37, v118, v36
	v_cvt_pk_bf16_f32 v40, v44, v45
	v_cvt_pk_bf16_f32 v41, v46, v47
	global_store_dwordx4 v[62:63], v[38:41], off offset:256 nt
	s_and_saveexec_b64 s[24:25], s[40:41]
	s_cbranch_execz .LBB0_815
	v_lshl_add_u64 v[38:39], v[52:53], 2, s[46:47]
	s_waitcnt lgkmcnt(0)
	v_add_f32_e32 v36, v36, v37
	global_atomic_add_f32 v[38:39], v36, off
.LBB0_815:
	s_or_b64 exec, exec, s[24:25]
	v_add_u32_e32 v36, 0xa0, v140
	s_waitcnt lgkmcnt(0)
	v_ashrrev_i32_e32 v37, 31, v36
	v_lshlrev_b64 v[38:39], 10, v[36:37]
	v_lshl_add_u64 v[46:47], v[38:39], 0, v[138:139]
	v_lshlrev_b64 v[48:49], 2, v[46:47]
	v_lshl_add_u64 v[50:51], s[28:29], 0, v[48:49]
	global_load_dwordx4 v[38:41], v[50:51], off
	global_load_dwordx4 v[42:45], v[50:51], off offset:16
	v_lshl_add_u64 v[46:47], v[46:47], 1, s[50:51]
	v_lshl_add_u64 v[48:49], s[44:45], 0, v[48:49]
	s_waitcnt vmcnt(1)
	v_pk_add_f32 v[34:35], v[34:35], v[40:41]
	v_pk_add_f32 v[32:33], v[32:33], v[38:39]
	s_waitcnt vmcnt(0)
	v_pk_add_f32 v[30:31], v[30:31], v[44:45]
	v_pk_add_f32 v[28:29], v[28:29], v[42:43]
	global_store_dwordx4 v[48:49], v[32:35], off nt
	global_store_dwordx4 v[48:49], v[28:31], off offset:16 nt
	v_cvt_pk_bf16_f32 v38, v32, v33
	v_cvt_pk_bf16_f32 v39, v34, v35
	v_cvt_pk_bf16_f32 v40, v28, v29
	v_cvt_pk_bf16_f32 v41, v30, v31
	global_store_dwordx4 v[46:47], v[38:41], off nt
	global_load_dwordx4 v[38:41], v[50:51], off offset:512
	s_nop 0
	global_load_dwordx4 v[42:45], v[50:51], off offset:528
	v_mul_f32_e32 v33, v33, v33
	v_mul_f32_e32 v35, v35, v35
	v_mul_f32_e32 v29, v29, v29
	v_mul_f32_e32 v31, v31, v31
	v_fmac_f32_e32 v33, v32, v32
	v_fmac_f32_e32 v35, v34, v34
	v_fmac_f32_e32 v29, v28, v28
	v_fmac_f32_e32 v31, v30, v30
	v_add_f32_e32 v28, v33, v35
	v_add_f32_e32 v29, v29, v31
	v_add_f32_e32 v32, v28, v29
	s_waitcnt vmcnt(1)
	v_pk_add_f32 v[26:27], v[26:27], v[40:41]
	v_pk_add_f32 v[24:25], v[24:25], v[38:39]
	s_waitcnt vmcnt(0)
	v_pk_add_f32 v[30:31], v[22:23], v[44:45]
	v_pk_add_f32 v[28:29], v[20:21], v[42:43]
	v_mul_f32_e32 v20, v25, v25
	v_mul_f32_e32 v21, v27, v27
	v_mul_f32_e32 v22, v29, v29
	v_mul_f32_e32 v23, v31, v31
	v_fmac_f32_e32 v20, v24, v24
	v_fmac_f32_e32 v21, v26, v26
	v_fmac_f32_e32 v22, v28, v28
	v_fmac_f32_e32 v23, v30, v30
	v_add_f32_e32 v20, v20, v21
	v_add_f32_e32 v21, v22, v23
	v_add_f32_e32 v20, v20, v21
	v_add_f32_e32 v20, v32, v20
	ds_bpermute_b32 v21, v124, v20
	global_store_dwordx4 v[48:49], v[24:27], off offset:512 nt
	global_store_dwordx4 v[48:49], v[28:31], off offset:528 nt
	v_cvt_pk_bf16_f32 v22, v24, v25
	v_cvt_pk_bf16_f32 v23, v26, v27
	s_waitcnt lgkmcnt(0)
	v_add_f32_e32 v20, v20, v21
	ds_bpermute_b32 v21, v118, v20
	v_cvt_pk_bf16_f32 v24, v28, v29
	v_cvt_pk_bf16_f32 v25, v30, v31
	global_store_dwordx4 v[46:47], v[22:25], off offset:256 nt
	s_and_saveexec_b64 s[24:25], s[40:41]
	s_cbranch_execz .LBB0_817
	v_lshl_add_u64 v[22:23], v[36:37], 2, s[46:47]
	s_waitcnt lgkmcnt(0)
	v_add_f32_e32 v20, v20, v21
	global_atomic_add_f32 v[22:23], v20, off
.LBB0_817:
	s_or_b64 exec, exec, s[24:25]
	v_add_u32_e32 v20, 0xb0, v140
	s_waitcnt lgkmcnt(0)
	v_ashrrev_i32_e32 v21, 31, v20
	v_lshlrev_b64 v[22:23], 10, v[20:21]
	v_lshl_add_u64 v[30:31], v[22:23], 0, v[138:139]
	v_lshlrev_b64 v[32:33], 2, v[30:31]
	v_lshl_add_u64 v[34:35], s[28:29], 0, v[32:33]
	global_load_dwordx4 v[22:25], v[34:35], off
	global_load_dwordx4 v[26:29], v[34:35], off offset:16
	v_lshl_add_u64 v[30:31], v[30:31], 1, s[50:51]
	v_lshl_add_u64 v[32:33], s[44:45], 0, v[32:33]
	s_waitcnt vmcnt(1)
	v_pk_add_f32 v[18:19], v[18:19], v[24:25]
	v_pk_add_f32 v[16:17], v[16:17], v[22:23]
	s_waitcnt vmcnt(0)
	v_pk_add_f32 v[14:15], v[14:15], v[28:29]
	v_pk_add_f32 v[12:13], v[12:13], v[26:27]
	global_store_dwordx4 v[32:33], v[16:19], off nt
	global_store_dwordx4 v[32:33], v[12:15], off offset:16 nt
	v_cvt_pk_bf16_f32 v22, v16, v17
	v_cvt_pk_bf16_f32 v23, v18, v19
	v_cvt_pk_bf16_f32 v24, v12, v13
	v_cvt_pk_bf16_f32 v25, v14, v15
	global_store_dwordx4 v[30:31], v[22:25], off nt
	global_load_dwordx4 v[22:25], v[34:35], off offset:512
	s_nop 0
	global_load_dwordx4 v[26:29], v[34:35], off offset:528
	v_mul_f32_e32 v17, v17, v17
	v_mul_f32_e32 v19, v19, v19
	v_mul_f32_e32 v13, v13, v13
	v_mul_f32_e32 v15, v15, v15
	v_fmac_f32_e32 v17, v16, v16
	v_fmac_f32_e32 v19, v18, v18
	v_fmac_f32_e32 v13, v12, v12
	v_fmac_f32_e32 v15, v14, v14
	v_add_f32_e32 v12, v17, v19
	v_add_f32_e32 v13, v13, v15
	v_add_f32_e32 v16, v12, v13
	s_waitcnt vmcnt(1)
	v_pk_add_f32 v[10:11], v[10:11], v[24:25]
	v_pk_add_f32 v[8:9], v[8:9], v[22:23]
	s_waitcnt vmcnt(0)
	v_pk_add_f32 v[14:15], v[6:7], v[28:29]
	v_pk_add_f32 v[12:13], v[4:5], v[26:27]
	v_mul_f32_e32 v4, v9, v9
	v_mul_f32_e32 v5, v11, v11
	v_mul_f32_e32 v6, v13, v13
	v_mul_f32_e32 v7, v15, v15
	v_fmac_f32_e32 v4, v8, v8
	v_fmac_f32_e32 v5, v10, v10
	v_fmac_f32_e32 v6, v12, v12
	v_fmac_f32_e32 v7, v14, v14
	v_add_f32_e32 v4, v4, v5
	v_add_f32_e32 v5, v6, v7
	v_add_f32_e32 v4, v4, v5
	v_add_f32_e32 v4, v16, v4
	ds_bpermute_b32 v5, v124, v4
	global_store_dwordx4 v[32:33], v[8:11], off offset:512 nt
	global_store_dwordx4 v[32:33], v[12:15], off offset:528 nt
	v_cvt_pk_bf16_f32 v6, v8, v9
	v_cvt_pk_bf16_f32 v7, v10, v11
	s_waitcnt lgkmcnt(0)
	v_add_f32_e32 v4, v4, v5
	ds_bpermute_b32 v5, v118, v4
	v_cvt_pk_bf16_f32 v8, v12, v13
	v_cvt_pk_bf16_f32 v9, v14, v15
	global_store_dwordx4 v[30:31], v[6:9], off offset:256 nt
	s_and_saveexec_b64 s[24:25], s[40:41]
	s_cbranch_execz .LBB0_819
	v_lshl_add_u64 v[6:7], v[20:21], 2, s[46:47]
	s_waitcnt lgkmcnt(0)
	v_add_f32_e32 v4, v4, v5
	global_atomic_add_f32 v[6:7], v4, off

.LBB0_892:
	v_lshl_add_u32 v144, s71, 8, v3
	v_ashrrev_i32_e32 v145, 31, v144
	v_lshl_add_u64 v[140:141], v[144:145], 2, s[44:45]
	global_load_dword v246, v[140:141], off
	global_load_dword v247, v[140:141], off offset:64
	global_load_dword v248, v[140:141], off offset:128
	global_load_dword v249, v[140:141], off offset:192
	global_load_dword v250, v[140:141], off offset:512
	global_load_dword v251, v[140:141], off offset:576
	global_load_dword v252, v[140:141], off offset:640
	global_load_dword v253, v[140:141], off offset:704
	v_lshl_or_b32 v138, s70, 8, v147
	v_ashrrev_i32_e32 v139, 31, v138
	s_mov_b64 s[24:25], 0x100000
	s_mov_b64 s[28:29], -1
	s_waitcnt vmcnt(7)
	s_nop 1
	v_fmamk_f32 v142, v246, 0x3a800000, v202
	v_rsq_f32_e32 v150, v142
	v_lshlrev_b64 v[142:143], 13, v[144:145]
	v_lshl_add_u64 v[152:153], s[46:47], 0, v[142:143]
	v_lshlrev_b64 v[142:143], 1, v[138:139]
	v_pk_mul_f32 v[124:125], v[124:125], v[150:151] op_sel_hi:[1,0]
	v_pk_mul_f32 v[128:129], v[128:129], v[150:151] op_sel_hi:[1,0]
	v_pk_mul_f32 v[126:127], v[126:127], v[150:151] op_sel_hi:[1,0]
	v_max_f32_e32 v124, 0, v124
	v_pk_mul_f32 v[130:131], v[130:131], v[150:151] op_sel_hi:[1,0]
	v_mul_f32_e32 v145, v124, v124
	v_max_f32_e32 v124, 0, v129
	v_max_f32_e32 v125, 0, v125
	v_max_f32_e32 v126, 0, v126
	v_max_f32_e32 v128, 0, v128
	v_mul_f32_e32 v124, v124, v124
	v_mul_f32_e32 v129, v125, v125
	v_max_f32_e32 v125, 0, v130
	v_mul_f32_e32 v130, v126, v126
	v_max_f32_e32 v126, 0, v131
	v_max_f32_e32 v127, 0, v127
	v_pk_mul_f32 v[116:117], v[116:117], v[150:151] op_sel_hi:[1,0]
	v_lshl_add_u64 v[138:139], v[152:153], 0, v[142:143]
	v_mul_f32_e32 v128, v128, v128
	v_mul_f32_e32 v125, v125, v125
	v_mul_f32_e32 v126, v126, v126
	v_mul_f32_e32 v127, v127, v127
	v_cvt_pk_bf16_f32 v124, v128, v124
	v_pk_mul_f32 v[120:121], v[120:121], v[150:151] op_sel_hi:[1,0]
	v_pk_mul_f32 v[118:119], v[118:119], v[150:151] op_sel_hi:[1,0]
	v_max_f32_e32 v116, 0, v116
	v_cvt_pk_bf16_f32 v125, v125, v126
	v_cvt_pk_bf16_f32 v126, v145, v129
	v_cvt_pk_bf16_f32 v127, v130, v127
	global_store_dwordx4 v[138:139], v[124:127], off nt
	v_pk_mul_f32 v[122:123], v[122:123], v[150:151] op_sel_hi:[1,0]
	v_max_f32_e32 v117, 0, v117
	v_mul_f32_e32 v124, v116, v116
	v_max_f32_e32 v116, 0, v121
	v_max_f32_e32 v118, 0, v118
	v_max_f32_e32 v120, 0, v120
	v_mul_f32_e32 v116, v116, v116
	v_mul_f32_e32 v121, v117, v117
	v_max_f32_e32 v117, 0, v122
	v_mul_f32_e32 v122, v118, v118
	v_max_f32_e32 v118, 0, v123
	v_max_f32_e32 v119, 0, v119
	v_mul_f32_e32 v120, v120, v120
	v_mul_f32_e32 v117, v117, v117
	v_mul_f32_e32 v118, v118, v118
	v_mul_f32_e32 v119, v119, v119
	v_cvt_pk_bf16_f32 v116, v120, v116
	v_cvt_pk_bf16_f32 v117, v117, v118
	v_cvt_pk_bf16_f32 v118, v124, v121
	v_cvt_pk_bf16_f32 v119, v122, v119
	global_store_dwordx4 v[138:139], v[116:119], off offset:256 nt
	s_nop 1
	v_or_b32_e32 v116, 16, v144
	v_ashrrev_i32_e32 v117, 31, v116
	s_nop 0
	v_lshlrev_b64 v[116:117], 13, v[116:117]
	v_lshl_add_u64 v[116:117], s[46:47], 0, v[116:117]
	v_lshl_add_u64 v[116:117], v[116:117], 0, v[142:143]
	s_waitcnt vmcnt(8)
	s_nop 1
	v_fmamk_f32 v118, v247, 0x3a800000, v202
	v_rsq_f32_e32 v118, v118
	s_nop 0
	v_pk_mul_f32 v[108:109], v[108:109], v[118:119] op_sel_hi:[1,0]
	v_pk_mul_f32 v[112:113], v[112:113], v[118:119] op_sel_hi:[1,0]
	v_pk_mul_f32 v[110:111], v[110:111], v[118:119] op_sel_hi:[1,0]
	v_max_f32_e32 v108, 0, v108
	v_pk_mul_f32 v[114:115], v[114:115], v[118:119] op_sel_hi:[1,0]
	v_mul_f32_e32 v119, v108, v108
	v_max_f32_e32 v108, 0, v113
	v_max_f32_e32 v109, 0, v109
	v_max_f32_e32 v110, 0, v110
	v_max_f32_e32 v112, 0, v112
	v_mul_f32_e32 v108, v108, v108
	v_mul_f32_e32 v113, v109, v109
	v_max_f32_e32 v109, 0, v114
	v_mul_f32_e32 v114, v110, v110
	v_max_f32_e32 v110, 0, v115
	v_max_f32_e32 v111, 0, v111
	v_pk_mul_f32 v[100:101], v[100:101], v[118:119] op_sel_hi:[1,0]
	v_mul_f32_e32 v112, v112, v112
	v_mul_f32_e32 v109, v109, v109
	v_mul_f32_e32 v110, v110, v110
	v_mul_f32_e32 v111, v111, v111
	v_cvt_pk_bf16_f32 v108, v112, v108
	v_pk_mul_f32 v[104:105], v[104:105], v[118:119] op_sel_hi:[1,0]
	v_pk_mul_f32 v[102:103], v[102:103], v[118:119] op_sel_hi:[1,0]
	v_max_f32_e32 v100, 0, v100
	v_cvt_pk_bf16_f32 v109, v109, v110
	v_cvt_pk_bf16_f32 v110, v119, v113
	v_cvt_pk_bf16_f32 v111, v114, v111
	global_store_dwordx4 v[116:117], v[108:111], off nt
	v_pk_mul_f32 v[106:107], v[106:107], v[118:119] op_sel_hi:[1,0]
	v_max_f32_e32 v101, 0, v101
	v_mul_f32_e32 v108, v100, v100
	v_max_f32_e32 v100, 0, v105
	v_max_f32_e32 v102, 0, v102
	v_max_f32_e32 v104, 0, v104
	v_mul_f32_e32 v100, v100, v100
	v_mul_f32_e32 v105, v101, v101
	v_max_f32_e32 v101, 0, v106
	v_mul_f32_e32 v106, v102, v102
	v_max_f32_e32 v102, 0, v107
	v_max_f32_e32 v103, 0, v103
	v_mul_f32_e32 v104, v104, v104
	v_mul_f32_e32 v101, v101, v101
	v_mul_f32_e32 v102, v102, v102
	v_mul_f32_e32 v103, v103, v103
	v_cvt_pk_bf16_f32 v100, v104, v100
	v_cvt_pk_bf16_f32 v101, v101, v102
	v_cvt_pk_bf16_f32 v102, v108, v105
	v_cvt_pk_bf16_f32 v103, v106, v103
	global_store_dwordx4 v[116:117], v[100:103], off offset:256 nt
	s_nop 1
	v_or_b32_e32 v100, 32, v144
	v_ashrrev_i32_e32 v101, 31, v100
	s_nop 0
	v_lshlrev_b64 v[100:101], 13, v[100:101]
	v_lshl_add_u64 v[100:101], s[46:47], 0, v[100:101]
	v_lshl_add_u64 v[100:101], v[100:101], 0, v[142:143]
	s_waitcnt vmcnt(9)
	s_nop 1
	v_fmamk_f32 v102, v248, 0x3a800000, v202
	v_rsq_f32_e32 v102, v102
	s_nop 0
	v_pk_mul_f32 v[92:93], v[92:93], v[102:103] op_sel_hi:[1,0]
	v_pk_mul_f32 v[96:97], v[96:97], v[102:103] op_sel_hi:[1,0]
	v_pk_mul_f32 v[94:95], v[94:95], v[102:103] op_sel_hi:[1,0]
	v_max_f32_e32 v92, 0, v92
	v_pk_mul_f32 v[98:99], v[98:99], v[102:103] op_sel_hi:[1,0]
	v_mul_f32_e32 v103, v92, v92
	v_max_f32_e32 v92, 0, v97
	v_max_f32_e32 v93, 0, v93
	v_max_f32_e32 v94, 0, v94
	v_max_f32_e32 v96, 0, v96
	v_mul_f32_e32 v92, v92, v92
	v_mul_f32_e32 v97, v93, v93
	v_max_f32_e32 v93, 0, v98
	v_mul_f32_e32 v98, v94, v94
	v_max_f32_e32 v94, 0, v99
	v_max_f32_e32 v95, 0, v95
	v_pk_mul_f32 v[84:85], v[84:85], v[102:103] op_sel_hi:[1,0]
	v_mul_f32_e32 v96, v96, v96
	v_mul_f32_e32 v93, v93, v93
	v_mul_f32_e32 v94, v94, v94
	v_mul_f32_e32 v95, v95, v95
	v_cvt_pk_bf16_f32 v92, v96, v92
	v_pk_mul_f32 v[88:89], v[88:89], v[102:103] op_sel_hi:[1,0]
	v_pk_mul_f32 v[86:87], v[86:87], v[102:103] op_sel_hi:[1,0]
	v_max_f32_e32 v84, 0, v84
	v_cvt_pk_bf16_f32 v93, v93, v94
	v_cvt_pk_bf16_f32 v94, v103, v97
	v_cvt_pk_bf16_f32 v95, v98, v95
	global_store_dwordx4 v[100:101], v[92:95], off nt
	v_pk_mul_f32 v[90:91], v[90:91], v[102:103] op_sel_hi:[1,0]
	v_max_f32_e32 v85, 0, v85
	v_mul_f32_e32 v92, v84, v84
	v_max_f32_e32 v84, 0, v89
	v_max_f32_e32 v86, 0, v86
	v_max_f32_e32 v88, 0, v88
	v_mul_f32_e32 v84, v84, v84
	v_mul_f32_e32 v89, v85, v85
	v_max_f32_e32 v85, 0, v90
	v_mul_f32_e32 v90, v86, v86
	v_max_f32_e32 v86, 0, v91
	v_max_f32_e32 v87, 0, v87
	v_mul_f32_e32 v88, v88, v88
	v_mul_f32_e32 v85, v85, v85
	v_mul_f32_e32 v86, v86, v86
	v_mul_f32_e32 v87, v87, v87
	v_cvt_pk_bf16_f32 v84, v88, v84
	v_cvt_pk_bf16_f32 v85, v85, v86
	v_cvt_pk_bf16_f32 v86, v92, v89
	v_cvt_pk_bf16_f32 v87, v90, v87
	global_store_dwordx4 v[100:101], v[84:87], off offset:256 nt
	s_nop 1
	v_or_b32_e32 v84, 48, v144
	v_ashrrev_i32_e32 v85, 31, v84
	s_nop 0
	v_lshlrev_b64 v[84:85], 13, v[84:85]
	v_lshl_add_u64 v[84:85], s[46:47], 0, v[84:85]
	v_lshl_add_u64 v[84:85], v[84:85], 0, v[142:143]
	s_waitcnt vmcnt(10)
	s_nop 1
	v_fmamk_f32 v86, v249, 0x3a800000, v202
	v_rsq_f32_e32 v86, v86
	s_nop 0
	v_pk_mul_f32 v[76:77], v[76:77], v[86:87] op_sel_hi:[1,0]
	v_pk_mul_f32 v[80:81], v[80:81], v[86:87] op_sel_hi:[1,0]
	v_pk_mul_f32 v[78:79], v[78:79], v[86:87] op_sel_hi:[1,0]
	v_max_f32_e32 v76, 0, v76
	v_pk_mul_f32 v[82:83], v[82:83], v[86:87] op_sel_hi:[1,0]
	v_mul_f32_e32 v87, v76, v76
	v_max_f32_e32 v76, 0, v81
	v_max_f32_e32 v77, 0, v77
	v_max_f32_e32 v78, 0, v78
	v_max_f32_e32 v80, 0, v80
	v_mul_f32_e32 v76, v76, v76
	v_mul_f32_e32 v81, v77, v77
	v_max_f32_e32 v77, 0, v82
	v_mul_f32_e32 v82, v78, v78
	v_max_f32_e32 v78, 0, v83
	v_max_f32_e32 v79, 0, v79
	v_pk_mul_f32 v[70:71], v[70:71], v[86:87] op_sel_hi:[1,0]
	v_pk_mul_f32 v[68:69], v[68:69], v[86:87] op_sel_hi:[1,0]
	v_mul_f32_e32 v80, v80, v80
	v_mul_f32_e32 v77, v77, v77
	v_mul_f32_e32 v78, v78, v78
	v_mul_f32_e32 v79, v79, v79
	v_cvt_pk_bf16_f32 v76, v80, v76
	v_pk_mul_f32 v[74:75], v[74:75], v[86:87] op_sel_hi:[1,0]
	v_pk_mul_f32 v[72:73], v[72:73], v[86:87] op_sel_hi:[1,0]
	v_max_f32_e32 v68, 0, v68
	v_max_f32_e32 v69, 0, v69
	v_max_f32_e32 v70, 0, v70
	v_cvt_pk_bf16_f32 v77, v77, v78
	v_cvt_pk_bf16_f32 v78, v87, v81
	v_cvt_pk_bf16_f32 v79, v82, v79
	global_store_dwordx4 v[84:85], v[76:79], off nt
	v_max_f32_e32 v71, 0, v71
	v_max_f32_e32 v72, 0, v72
	v_mul_f32_e32 v76, v68, v68
	v_max_f32_e32 v68, 0, v73
	v_mul_f32_e32 v73, v69, v69
	v_max_f32_e32 v69, 0, v74
	v_mul_f32_e32 v74, v70, v70
	v_max_f32_e32 v70, 0, v75
	v_mul_f32_e32 v68, v68, v68
	v_mul_f32_e32 v69, v69, v69
	v_mul_f32_e32 v70, v70, v70
	v_mul_f32_e32 v71, v71, v71
	v_mul_f32_e32 v72, v72, v72
	v_cvt_pk_bf16_f32 v68, v72, v68
	v_cvt_pk_bf16_f32 v69, v69, v70
	v_cvt_pk_bf16_f32 v70, v76, v73
	v_cvt_pk_bf16_f32 v71, v74, v71
	global_store_dwordx4 v[84:85], v[68:71], off offset:256 nt
	s_nop 0
	s_waitcnt vmcnt(11)
	s_nop 1
	v_fmamk_f32 v68, v250, 0x3a800000, v202
	v_rsq_f32_e32 v70, v68
	v_lshl_add_u64 v[68:69], v[138:139], 0, s[24:25]
	s_mov_b32 s24, 0x100000
	v_pk_mul_f32 v[60:61], v[60:61], v[70:71] op_sel_hi:[1,0]
	v_pk_mul_f32 v[64:65], v[64:65], v[70:71] op_sel_hi:[1,0]
	v_pk_mul_f32 v[62:63], v[62:63], v[70:71] op_sel_hi:[1,0]
	v_max_f32_e32 v60, 0, v60
	v_pk_mul_f32 v[66:67], v[66:67], v[70:71] op_sel_hi:[1,0]
	v_max_f32_e32 v64, 0, v64
	v_mul_f32_e32 v71, v60, v60
	v_max_f32_e32 v60, 0, v65
	v_max_f32_e32 v61, 0, v61
	v_max_f32_e32 v62, 0, v62
	v_mul_f32_e32 v64, v64, v64
	v_mul_f32_e32 v60, v60, v60
	v_mul_f32_e32 v65, v61, v61
	v_max_f32_e32 v61, 0, v66
	v_mul_f32_e32 v66, v62, v62
	v_max_f32_e32 v62, 0, v67
	v_mul_f32_e32 v61, v61, v61
	v_max_f32_e32 v63, 0, v63
	v_mul_f32_e32 v62, v62, v62
	v_cvt_pk_bf16_f32 v60, v64, v60
	v_add_co_u32_e32 v64, vcc, s24, v138
	v_pk_mul_f32 v[54:55], v[54:55], v[70:71] op_sel_hi:[1,0]
	v_pk_mul_f32 v[52:53], v[52:53], v[70:71] op_sel_hi:[1,0]
	v_mul_f32_e32 v63, v63, v63
	v_cvt_pk_bf16_f32 v61, v61, v62
	v_cvt_pk_bf16_f32 v62, v71, v65
	v_addc_co_u32_e32 v65, vcc, 0, v139, vcc
	v_pk_mul_f32 v[58:59], v[58:59], v[70:71] op_sel_hi:[1,0]
	v_pk_mul_f32 v[56:57], v[56:57], v[70:71] op_sel_hi:[1,0]
	v_max_f32_e32 v52, 0, v52
	v_max_f32_e32 v53, 0, v53
	v_max_f32_e32 v54, 0, v54
	v_cvt_pk_bf16_f32 v63, v66, v63
	global_store_dwordx4 v[64:65], v[60:63], off nt
	v_max_f32_e32 v55, 0, v55
	v_max_f32_e32 v56, 0, v56
	v_mul_f32_e32 v60, v52, v52
	v_max_f32_e32 v52, 0, v57
	v_mul_f32_e32 v57, v53, v53
	v_max_f32_e32 v53, 0, v58
	v_mul_f32_e32 v58, v54, v54
	v_max_f32_e32 v54, 0, v59
	v_mul_f32_e32 v52, v52, v52
	v_mul_f32_e32 v53, v53, v53
	v_mul_f32_e32 v54, v54, v54
	v_mul_f32_e32 v55, v55, v55
	v_mul_f32_e32 v56, v56, v56
	v_cvt_pk_bf16_f32 v52, v56, v52
	v_cvt_pk_bf16_f32 v53, v53, v54
	v_cvt_pk_bf16_f32 v54, v60, v57
	v_cvt_pk_bf16_f32 v55, v58, v55
	global_store_dwordx4 v[68:69], v[52:55], off offset:256 nt
	s_nop 0
	s_mov_b64 s[24:25], 0x120000
	s_waitcnt vmcnt(12)
	s_nop 1
	v_fmamk_f32 v52, v251, 0x3a800000, v202
	v_rsq_f32_e32 v54, v52
	v_lshl_add_u64 v[52:53], v[138:139], 0, s[24:25]
	s_mov_b32 s24, 0x120000
	v_pk_mul_f32 v[44:45], v[44:45], v[54:55] op_sel_hi:[1,0]
	v_pk_mul_f32 v[48:49], v[48:49], v[54:55] op_sel_hi:[1,0]
	v_pk_mul_f32 v[46:47], v[46:47], v[54:55] op_sel_hi:[1,0]
	v_max_f32_e32 v44, 0, v44
	v_pk_mul_f32 v[50:51], v[50:51], v[54:55] op_sel_hi:[1,0]
	v_max_f32_e32 v48, 0, v48
	v_mul_f32_e32 v55, v44, v44
	v_max_f32_e32 v44, 0, v49
	v_max_f32_e32 v45, 0, v45
	v_max_f32_e32 v46, 0, v46
	v_mul_f32_e32 v48, v48, v48
	v_mul_f32_e32 v44, v44, v44
	v_mul_f32_e32 v49, v45, v45
	v_max_f32_e32 v45, 0, v50
	v_mul_f32_e32 v50, v46, v46
	v_max_f32_e32 v46, 0, v51
	v_mul_f32_e32 v45, v45, v45
	v_max_f32_e32 v47, 0, v47
	v_mul_f32_e32 v46, v46, v46
	v_cvt_pk_bf16_f32 v44, v48, v44
	v_add_co_u32_e32 v48, vcc, s24, v138
	v_pk_mul_f32 v[38:39], v[38:39], v[54:55] op_sel_hi:[1,0]
	v_pk_mul_f32 v[36:37], v[36:37], v[54:55] op_sel_hi:[1,0]
	v_mul_f32_e32 v47, v47, v47
	v_cvt_pk_bf16_f32 v45, v45, v46
	v_cvt_pk_bf16_f32 v46, v55, v49
	v_addc_co_u32_e32 v49, vcc, 0, v139, vcc
	v_pk_mul_f32 v[42:43], v[42:43], v[54:55] op_sel_hi:[1,0]
	v_pk_mul_f32 v[40:41], v[40:41], v[54:55] op_sel_hi:[1,0]
	v_max_f32_e32 v36, 0, v36
	v_max_f32_e32 v37, 0, v37
	v_max_f32_e32 v38, 0, v38
	v_cvt_pk_bf16_f32 v47, v50, v47
	global_store_dwordx4 v[48:49], v[44:47], off nt
	v_max_f32_e32 v39, 0, v39
	v_max_f32_e32 v40, 0, v40
	v_mul_f32_e32 v44, v36, v36
	v_max_f32_e32 v36, 0, v41
	v_mul_f32_e32 v41, v37, v37
	v_max_f32_e32 v37, 0, v42
	v_mul_f32_e32 v42, v38, v38
	v_max_f32_e32 v38, 0, v43
	v_mul_f32_e32 v36, v36, v36
	v_mul_f32_e32 v37, v37, v37
	v_mul_f32_e32 v38, v38, v38
	v_mul_f32_e32 v39, v39, v39
	v_mul_f32_e32 v40, v40, v40
	v_cvt_pk_bf16_f32 v36, v40, v36
	v_cvt_pk_bf16_f32 v37, v37, v38
	v_cvt_pk_bf16_f32 v38, v44, v41
	v_cvt_pk_bf16_f32 v39, v42, v39
	global_store_dwordx4 v[52:53], v[36:39], off offset:256 nt
	s_nop 0
	s_mov_b64 s[24:25], 0x140000
	s_waitcnt vmcnt(13)
	s_nop 1
	v_fmamk_f32 v36, v252, 0x3a800000, v202
	v_rsq_f32_e32 v38, v36
	v_lshl_add_u64 v[36:37], v[138:139], 0, s[24:25]
	s_mov_b32 s24, 0x140000
	v_pk_mul_f32 v[28:29], v[28:29], v[38:39] op_sel_hi:[1,0]
	v_pk_mul_f32 v[32:33], v[32:33], v[38:39] op_sel_hi:[1,0]
	v_pk_mul_f32 v[30:31], v[30:31], v[38:39] op_sel_hi:[1,0]
	v_max_f32_e32 v28, 0, v28
	v_pk_mul_f32 v[34:35], v[34:35], v[38:39] op_sel_hi:[1,0]
	v_max_f32_e32 v32, 0, v32
	v_mul_f32_e32 v39, v28, v28
	v_max_f32_e32 v28, 0, v33
	v_max_f32_e32 v29, 0, v29
	v_max_f32_e32 v30, 0, v30
	v_mul_f32_e32 v32, v32, v32
	v_mul_f32_e32 v28, v28, v28
	v_mul_f32_e32 v33, v29, v29
	v_max_f32_e32 v29, 0, v34
	v_mul_f32_e32 v34, v30, v30
	v_max_f32_e32 v30, 0, v35
	v_mul_f32_e32 v29, v29, v29
	v_max_f32_e32 v31, 0, v31
	v_mul_f32_e32 v30, v30, v30
	v_cvt_pk_bf16_f32 v28, v32, v28
	v_add_co_u32_e32 v32, vcc, s24, v138
	v_pk_mul_f32 v[22:23], v[22:23], v[38:39] op_sel_hi:[1,0]
	v_pk_mul_f32 v[20:21], v[20:21], v[38:39] op_sel_hi:[1,0]
	v_mul_f32_e32 v31, v31, v31
	v_cvt_pk_bf16_f32 v29, v29, v30
	v_cvt_pk_bf16_f32 v30, v39, v33
	v_addc_co_u32_e32 v33, vcc, 0, v139, vcc
	v_pk_mul_f32 v[26:27], v[26:27], v[38:39] op_sel_hi:[1,0]
	v_pk_mul_f32 v[24:25], v[24:25], v[38:39] op_sel_hi:[1,0]
	v_max_f32_e32 v20, 0, v20
	v_max_f32_e32 v21, 0, v21
	v_max_f32_e32 v22, 0, v22
	v_cvt_pk_bf16_f32 v31, v34, v31
	global_store_dwordx4 v[32:33], v[28:31], off nt
	v_max_f32_e32 v23, 0, v23
	v_max_f32_e32 v24, 0, v24
	v_mul_f32_e32 v28, v20, v20
	v_max_f32_e32 v20, 0, v25
	v_mul_f32_e32 v25, v21, v21
	v_max_f32_e32 v21, 0, v26
	v_mul_f32_e32 v26, v22, v22
	v_max_f32_e32 v22, 0, v27
	v_mul_f32_e32 v20, v20, v20
	v_mul_f32_e32 v21, v21, v21
	v_mul_f32_e32 v22, v22, v22
	v_mul_f32_e32 v23, v23, v23
	v_mul_f32_e32 v24, v24, v24
	v_cvt_pk_bf16_f32 v20, v24, v20
	v_cvt_pk_bf16_f32 v21, v21, v22
	v_cvt_pk_bf16_f32 v22, v28, v25
	v_cvt_pk_bf16_f32 v23, v26, v23
	global_store_dwordx4 v[36:37], v[20:23], off offset:256 nt
	s_nop 0
	s_mov_b64 s[24:25], 0x160000
	v_lshl_add_u64 v[22:23], v[138:139], 0, s[24:25]
	s_mov_b32 s24, 0x160000
	s_waitcnt vmcnt(14)
	s_nop 1
	v_fmamk_f32 v20, v253, 0x3a800000, v202
	v_rsq_f32_e32 v20, v20
	s_nop 0
	v_pk_mul_f32 v[12:13], v[12:13], v[20:21] op_sel_hi:[1,0]
	v_pk_mul_f32 v[16:17], v[16:17], v[20:21] op_sel_hi:[1,0]
	v_pk_mul_f32 v[14:15], v[14:15], v[20:21] op_sel_hi:[1,0]
	v_max_f32_e32 v12, 0, v12
	v_pk_mul_f32 v[18:19], v[18:19], v[20:21] op_sel_hi:[1,0]
	v_max_f32_e32 v16, 0, v16
	v_mul_f32_e32 v21, v12, v12
	v_max_f32_e32 v12, 0, v17
	v_max_f32_e32 v13, 0, v13
	v_max_f32_e32 v14, 0, v14
	v_mul_f32_e32 v16, v16, v16
	v_mul_f32_e32 v12, v12, v12
	v_mul_f32_e32 v17, v13, v13
	v_max_f32_e32 v13, 0, v18
	v_mul_f32_e32 v18, v14, v14
	v_max_f32_e32 v14, 0, v19
	v_mul_f32_e32 v13, v13, v13
	v_max_f32_e32 v15, 0, v15
	v_mul_f32_e32 v14, v14, v14
	v_cvt_pk_bf16_f32 v12, v16, v12
	v_add_co_u32_e32 v16, vcc, s24, v138
	v_pk_mul_f32 v[6:7], v[6:7], v[20:21] op_sel_hi:[1,0]
	v_pk_mul_f32 v[4:5], v[4:5], v[20:21] op_sel_hi:[1,0]
	v_mul_f32_e32 v15, v15, v15
	v_cvt_pk_bf16_f32 v13, v13, v14
	v_cvt_pk_bf16_f32 v14, v21, v17
	v_addc_co_u32_e32 v17, vcc, 0, v139, vcc
	v_pk_mul_f32 v[10:11], v[10:11], v[20:21] op_sel_hi:[1,0]
	v_pk_mul_f32 v[8:9], v[8:9], v[20:21] op_sel_hi:[1,0]
	v_max_f32_e32 v4, 0, v4
	v_max_f32_e32 v5, 0, v5
	v_max_f32_e32 v6, 0, v6
	v_cvt_pk_bf16_f32 v15, v18, v15
	global_store_dwordx4 v[16:17], v[12:15], off nt
	v_max_f32_e32 v7, 0, v7
	v_max_f32_e32 v8, 0, v8
	v_mul_f32_e32 v12, v4, v4
	v_max_f32_e32 v4, 0, v9
	v_mul_f32_e32 v9, v5, v5
	v_max_f32_e32 v5, 0, v10
	v_mul_f32_e32 v10, v6, v6
	v_max_f32_e32 v6, 0, v11
	v_mul_f32_e32 v4, v4, v4
	v_mul_f32_e32 v5, v5, v5
	v_mul_f32_e32 v6, v6, v6
	v_mul_f32_e32 v7, v7, v7
	s_andn2_b64 vcc, exec, s[40:41]
	v_mul_f32_e32 v8, v8, v8
	v_cvt_pk_bf16_f32 v4, v8, v4
	v_cvt_pk_bf16_f32 v5, v5, v6
	v_cvt_pk_bf16_f32 v6, v12, v9
	v_cvt_pk_bf16_f32 v7, v10, v7
	global_store_dwordx4 v[22:23], v[4:7], off offset:256 nt
	s_cbranch_vccnz .LBB0_881
	s_andn2_b64 vcc, exec, s[42:43]
	s_cbranch_vccnz .LBB0_880
	s_barrier
	s_branch .LBB0_880

.LBB0_964:
	v_lshl_add_u32 v140, s87, 8, v3
	v_lshl_or_b32 v138, s86, 8, v147
	v_ashrrev_i32_e32 v141, 31, v140
	v_ashrrev_i32_e32 v139, 31, v138
	v_lshlrev_b64 v[142:143], 10, v[140:141]
	v_lshl_add_u64 v[144:145], v[142:143], 0, v[138:139]
	v_lshl_add_u64 v[142:143], v[144:145], 2, s[44:45]
	global_load_dwordx4 v[150:153], v[142:143], off
	global_load_dwordx4 v[154:157], v[142:143], off offset:16
	s_mov_b64 s[24:25], -1
	s_and_b64 vcc, exec, s[0:1]
	s_waitcnt vmcnt(0)
	v_pk_add_f32 v[130:131], v[130:131], v[152:153]
	v_pk_add_f32 v[128:129], v[128:129], v[150:151]
	v_pk_add_f32 v[126:127], v[126:127], v[156:157]
	v_pk_add_f32 v[124:125], v[124:125], v[154:155]
	global_store_dwordx4 v[142:143], v[128:131], off nt
	global_store_dwordx4 v[142:143], v[124:127], off offset:16 nt
	s_cbranch_vccz .LBB0_966
	global_load_dwordx4 v[150:153], v[142:143], off offset:512
	global_load_dwordx4 v[154:157], v[142:143], off offset:528
	s_mov_b64 s[24:25], 0
	s_waitcnt vmcnt(1)
	v_pk_add_f32 v[152:153], v[122:123], v[152:153]
	v_pk_add_f32 v[150:151], v[120:121], v[150:151]
	s_waitcnt vmcnt(0)
	v_pk_add_f32 v[156:157], v[118:119], v[156:157]
	v_pk_add_f32 v[154:155], v[116:117], v[154:155]
	global_store_dwordx4 v[142:143], v[150:153], off offset:512 nt
	global_store_dwordx4 v[142:143], v[154:157], off offset:528 nt
.LBB0_966:
	s_andn2_b64 vcc, exec, s[24:25]
	v_xor_b32_e32 v150, 16, v204
	v_and_b32_e32 v151, 64, v204
	v_xor_b32_e32 v149, 32, v204
	s_cbranch_vccnz .LBB0_970
	v_mul_f32_e32 v152, v129, v129
	v_mul_f32_e32 v153, v131, v131
	v_fmac_f32_e32 v152, v128, v128
	v_fmac_f32_e32 v153, v130, v130
	v_lshl_add_u64 v[144:145], v[144:145], 1, s[48:49]
	v_add_f32_e32 v152, v152, v153
	v_mul_f32_e32 v153, v125, v125
	v_mul_f32_e32 v154, v127, v127
	v_cvt_pk_bf16_f32 v128, v128, v129
	v_cvt_pk_bf16_f32 v129, v130, v131
	v_cvt_pk_bf16_f32 v130, v124, v125
	v_cvt_pk_bf16_f32 v131, v126, v127
	global_store_dwordx4 v[144:145], v[128:131], off nt
	v_fmac_f32_e32 v153, v124, v124
	v_fmac_f32_e32 v154, v126, v126
	global_load_dwordx4 v[124:127], v[142:143], off offset:528
	global_load_dwordx4 v[128:131], v[142:143], off offset:512
	v_add_f32_e32 v153, v153, v154
	v_add_f32_e32 v152, v152, v153
	s_waitcnt vmcnt(1)
	v_pk_add_f32 v[116:117], v[116:117], v[124:125]
	s_waitcnt vmcnt(0)
	v_pk_add_f32 v[122:123], v[122:123], v[130:131]
	v_pk_add_f32 v[120:121], v[120:121], v[128:129]
	v_mul_f32_e32 v125, v123, v123
	v_mul_f32_e32 v124, v121, v121
	v_pk_add_f32 v[118:119], v[118:119], v[126:127]
	v_fmac_f32_e32 v124, v120, v120
	v_fmac_f32_e32 v125, v122, v122
	v_add_f32_e32 v124, v124, v125
	v_mul_f32_e32 v125, v117, v117
	v_mul_f32_e32 v126, v119, v119
	global_store_dwordx4 v[142:143], v[120:123], off offset:512 nt
	global_store_dwordx4 v[142:143], v[116:119], off offset:528 nt
	v_fmac_f32_e32 v125, v116, v116
	v_fmac_f32_e32 v126, v118, v118
	v_cvt_pk_bf16_f32 v120, v120, v121
	v_cvt_pk_bf16_f32 v121, v122, v123
	v_cvt_pk_bf16_f32 v122, v116, v117
	v_add_u32_e32 v117, 64, v151
	v_add_f32_e32 v125, v125, v126
	v_cmp_lt_i32_e32 vcc, v150, v117
	v_add_f32_e32 v124, v124, v125
	v_add_f32_e32 v124, v152, v124
	v_cndmask_b32_e32 v116, v204, v150, vcc
	v_lshlrev_b32_e32 v116, 2, v116
	ds_bpermute_b32 v116, v116, v124
	v_cmp_lt_i32_e32 vcc, v149, v117
	v_cvt_pk_bf16_f32 v123, v118, v119
	global_store_dwordx4 v[144:145], v[120:123], off offset:256 nt
	s_waitcnt lgkmcnt(0)
	v_add_f32_e32 v116, v124, v116
	v_cndmask_b32_e32 v117, v204, v149, vcc
	v_lshlrev_b32_e32 v117, 2, v117
	ds_bpermute_b32 v117, v117, v116
	s_and_saveexec_b64 s[24:25], s[38:39]
	s_cbranch_execz .LBB0_969
	v_lshl_add_u64 v[118:119], v[140:141], 2, s[46:47]
	s_waitcnt lgkmcnt(0)
	v_add_f32_e32 v116, v116, v117
	global_atomic_add_f32 v[118:119], v116, off

.LBB0_970:
	v_or_b32_e32 v116, 16, v140
	s_waitcnt lgkmcnt(0)
	v_ashrrev_i32_e32 v117, 31, v116
	v_lshlrev_b64 v[118:119], 10, v[116:117]
	v_lshl_add_u64 v[120:121], v[118:119], 0, v[138:139]
	v_lshl_add_u64 v[118:119], v[120:121], 2, s[44:45]
	global_load_dwordx4 v[122:125], v[118:119], off
	global_load_dwordx4 v[126:129], v[118:119], off offset:16
	s_mov_b64 s[24:25], -1
	s_and_b64 vcc, exec, s[0:1]
	s_waitcnt vmcnt(1)
	v_pk_add_f32 v[114:115], v[114:115], v[124:125]
	v_pk_add_f32 v[112:113], v[112:113], v[122:123]
	s_waitcnt vmcnt(0)
	v_pk_add_f32 v[110:111], v[110:111], v[128:129]
	v_pk_add_f32 v[108:109], v[108:109], v[126:127]
	global_store_dwordx4 v[118:119], v[112:115], off nt
	global_store_dwordx4 v[118:119], v[108:111], off offset:16 nt
	s_cbranch_vccz .LBB0_972
	global_load_dwordx4 v[122:125], v[118:119], off offset:512
	global_load_dwordx4 v[126:129], v[118:119], off offset:528
	s_mov_b64 s[24:25], 0
	s_waitcnt vmcnt(1)
	v_pk_add_f32 v[124:125], v[106:107], v[124:125]
	v_pk_add_f32 v[122:123], v[104:105], v[122:123]
	s_waitcnt vmcnt(0)
	v_pk_add_f32 v[128:129], v[102:103], v[128:129]
	v_pk_add_f32 v[126:127], v[100:101], v[126:127]
	global_store_dwordx4 v[118:119], v[122:125], off offset:512 nt
	global_store_dwordx4 v[118:119], v[126:129], off offset:528 nt
.LBB0_972:
	s_andn2_b64 vcc, exec, s[24:25]
	s_cbranch_vccnz .LBB0_976
	v_mul_f32_e32 v122, v113, v113
	v_mul_f32_e32 v123, v115, v115
	v_fmac_f32_e32 v122, v112, v112
	v_fmac_f32_e32 v123, v114, v114
	v_lshl_add_u64 v[120:121], v[120:121], 1, s[48:49]
	v_add_f32_e32 v122, v122, v123
	v_mul_f32_e32 v123, v109, v109
	v_mul_f32_e32 v124, v111, v111
	v_cvt_pk_bf16_f32 v112, v112, v113
	v_cvt_pk_bf16_f32 v113, v114, v115
	v_cvt_pk_bf16_f32 v114, v108, v109
	v_cvt_pk_bf16_f32 v115, v110, v111
	global_store_dwordx4 v[120:121], v[112:115], off nt
	v_fmac_f32_e32 v123, v108, v108
	v_fmac_f32_e32 v124, v110, v110
	global_load_dwordx4 v[108:111], v[118:119], off offset:528
	global_load_dwordx4 v[112:115], v[118:119], off offset:512
	v_add_f32_e32 v123, v123, v124
	v_add_f32_e32 v122, v122, v123
	s_waitcnt vmcnt(1)
	v_pk_add_f32 v[100:101], v[100:101], v[108:109]
	s_waitcnt vmcnt(0)
	v_pk_add_f32 v[106:107], v[106:107], v[114:115]
	v_pk_add_f32 v[104:105], v[104:105], v[112:113]
	v_mul_f32_e32 v109, v107, v107
	v_mul_f32_e32 v108, v105, v105
	v_pk_add_f32 v[102:103], v[102:103], v[110:111]
	v_fmac_f32_e32 v108, v104, v104
	v_fmac_f32_e32 v109, v106, v106
	v_add_f32_e32 v108, v108, v109
	v_mul_f32_e32 v109, v101, v101
	v_mul_f32_e32 v110, v103, v103
	global_store_dwordx4 v[118:119], v[104:107], off offset:512 nt
	global_store_dwordx4 v[118:119], v[100:103], off offset:528 nt
	v_fmac_f32_e32 v109, v100, v100
	v_fmac_f32_e32 v110, v102, v102
	v_cvt_pk_bf16_f32 v104, v104, v105
	v_cvt_pk_bf16_f32 v105, v106, v107
	v_cvt_pk_bf16_f32 v106, v100, v101
	v_add_u32_e32 v101, 64, v151
	v_add_f32_e32 v109, v109, v110
	v_cmp_lt_i32_e32 vcc, v150, v101
	v_add_f32_e32 v108, v108, v109
	v_add_f32_e32 v108, v122, v108
	v_cndmask_b32_e32 v100, v204, v150, vcc
	v_lshlrev_b32_e32 v100, 2, v100
	ds_bpermute_b32 v100, v100, v108
	v_cmp_lt_i32_e32 vcc, v149, v101
	v_cvt_pk_bf16_f32 v107, v102, v103
	global_store_dwordx4 v[120:121], v[104:107], off offset:256 nt
	s_waitcnt lgkmcnt(0)
	v_add_f32_e32 v100, v108, v100
	v_cndmask_b32_e32 v101, v204, v149, vcc
	v_lshlrev_b32_e32 v101, 2, v101
	ds_bpermute_b32 v101, v101, v100
	s_and_saveexec_b64 s[24:25], s[38:39]
	s_cbranch_execz .LBB0_975
	v_lshl_add_u64 v[102:103], v[116:117], 2, s[46:47]
	s_waitcnt lgkmcnt(0)
	v_add_f32_e32 v100, v100, v101
	global_atomic_add_f32 v[102:103], v100, off

.LBB0_976:
	v_or_b32_e32 v100, 32, v140
	s_waitcnt lgkmcnt(0)
	v_ashrrev_i32_e32 v101, 31, v100
	v_lshlrev_b64 v[102:103], 10, v[100:101]
	v_lshl_add_u64 v[104:105], v[102:103], 0, v[138:139]
	v_lshl_add_u64 v[102:103], v[104:105], 2, s[44:45]
	global_load_dwordx4 v[106:109], v[102:103], off
	global_load_dwordx4 v[110:113], v[102:103], off offset:16
	s_mov_b64 s[24:25], -1
	s_and_b64 vcc, exec, s[0:1]
	s_waitcnt vmcnt(1)
	v_pk_add_f32 v[98:99], v[98:99], v[108:109]
	v_pk_add_f32 v[96:97], v[96:97], v[106:107]
	s_waitcnt vmcnt(0)
	v_pk_add_f32 v[94:95], v[94:95], v[112:113]
	v_pk_add_f32 v[92:93], v[92:93], v[110:111]
	global_store_dwordx4 v[102:103], v[96:99], off nt
	global_store_dwordx4 v[102:103], v[92:95], off offset:16 nt
	s_cbranch_vccz .LBB0_978
	global_load_dwordx4 v[106:109], v[102:103], off offset:512
	global_load_dwordx4 v[110:113], v[102:103], off offset:528
	s_mov_b64 s[24:25], 0
	s_waitcnt vmcnt(1)
	v_pk_add_f32 v[108:109], v[90:91], v[108:109]
	v_pk_add_f32 v[106:107], v[88:89], v[106:107]
	s_waitcnt vmcnt(0)
	v_pk_add_f32 v[112:113], v[86:87], v[112:113]
	v_pk_add_f32 v[110:111], v[84:85], v[110:111]
	global_store_dwordx4 v[102:103], v[106:109], off offset:512 nt
	global_store_dwordx4 v[102:103], v[110:113], off offset:528 nt
.LBB0_978:
	s_andn2_b64 vcc, exec, s[24:25]
	s_cbranch_vccnz .LBB0_982
	v_mul_f32_e32 v106, v97, v97
	v_mul_f32_e32 v107, v99, v99
	v_fmac_f32_e32 v106, v96, v96
	v_fmac_f32_e32 v107, v98, v98
	v_lshl_add_u64 v[104:105], v[104:105], 1, s[48:49]
	v_add_f32_e32 v106, v106, v107
	v_mul_f32_e32 v107, v93, v93
	v_mul_f32_e32 v108, v95, v95
	v_cvt_pk_bf16_f32 v96, v96, v97
	v_cvt_pk_bf16_f32 v97, v98, v99
	v_cvt_pk_bf16_f32 v98, v92, v93
	v_cvt_pk_bf16_f32 v99, v94, v95
	global_store_dwordx4 v[104:105], v[96:99], off nt
	v_fmac_f32_e32 v107, v92, v92
	v_fmac_f32_e32 v108, v94, v94
	global_load_dwordx4 v[92:95], v[102:103], off offset:528
	global_load_dwordx4 v[96:99], v[102:103], off offset:512
	v_add_f32_e32 v107, v107, v108
	v_add_f32_e32 v106, v106, v107
	s_waitcnt vmcnt(1)
	v_pk_add_f32 v[84:85], v[84:85], v[92:93]
	s_waitcnt vmcnt(0)
	v_pk_add_f32 v[90:91], v[90:91], v[98:99]
	v_pk_add_f32 v[88:89], v[88:89], v[96:97]
	v_mul_f32_e32 v93, v91, v91
	v_mul_f32_e32 v92, v89, v89
	v_pk_add_f32 v[86:87], v[86:87], v[94:95]
	v_fmac_f32_e32 v92, v88, v88
	v_fmac_f32_e32 v93, v90, v90
	v_add_f32_e32 v92, v92, v93
	v_mul_f32_e32 v93, v85, v85
	v_mul_f32_e32 v94, v87, v87
	global_store_dwordx4 v[102:103], v[88:91], off offset:512 nt
	global_store_dwordx4 v[102:103], v[84:87], off offset:528 nt
	v_fmac_f32_e32 v93, v84, v84
	v_fmac_f32_e32 v94, v86, v86
	v_cvt_pk_bf16_f32 v88, v88, v89
	v_cvt_pk_bf16_f32 v89, v90, v91
	v_cvt_pk_bf16_f32 v90, v84, v85
	v_add_u32_e32 v85, 64, v151
	v_add_f32_e32 v93, v93, v94
	v_cmp_lt_i32_e32 vcc, v150, v85
	v_add_f32_e32 v92, v92, v93
	v_add_f32_e32 v92, v106, v92
	v_cndmask_b32_e32 v84, v204, v150, vcc
	v_lshlrev_b32_e32 v84, 2, v84
	ds_bpermute_b32 v84, v84, v92
	v_cmp_lt_i32_e32 vcc, v149, v85
	v_cvt_pk_bf16_f32 v91, v86, v87
	global_store_dwordx4 v[104:105], v[88:91], off offset:256 nt
	s_waitcnt lgkmcnt(0)
	v_add_f32_e32 v84, v92, v84
	v_cndmask_b32_e32 v85, v204, v149, vcc
	v_lshlrev_b32_e32 v85, 2, v85
	ds_bpermute_b32 v85, v85, v84
	s_and_saveexec_b64 s[24:25], s[38:39]
	s_cbranch_execz .LBB0_981
	v_lshl_add_u64 v[86:87], v[100:101], 2, s[46:47]
	s_waitcnt lgkmcnt(0)
	v_add_f32_e32 v84, v84, v85
	global_atomic_add_f32 v[86:87], v84, off

.LBB0_982:
	v_or_b32_e32 v84, 48, v140
	s_waitcnt lgkmcnt(0)
	v_ashrrev_i32_e32 v85, 31, v84
	v_lshlrev_b64 v[86:87], 10, v[84:85]
	v_lshl_add_u64 v[88:89], v[86:87], 0, v[138:139]
	v_lshl_add_u64 v[86:87], v[88:89], 2, s[44:45]
	global_load_dwordx4 v[90:93], v[86:87], off
	global_load_dwordx4 v[94:97], v[86:87], off offset:16
	s_mov_b64 s[24:25], -1
	s_and_b64 vcc, exec, s[0:1]
	s_waitcnt vmcnt(1)
	v_pk_add_f32 v[82:83], v[82:83], v[92:93]
	v_pk_add_f32 v[80:81], v[80:81], v[90:91]
	s_waitcnt vmcnt(0)
	v_pk_add_f32 v[78:79], v[78:79], v[96:97]
	v_pk_add_f32 v[76:77], v[76:77], v[94:95]
	global_store_dwordx4 v[86:87], v[80:83], off nt
	global_store_dwordx4 v[86:87], v[76:79], off offset:16 nt
	s_cbranch_vccz .LBB0_984
	global_load_dwordx4 v[90:93], v[86:87], off offset:512
	global_load_dwordx4 v[94:97], v[86:87], off offset:528
	s_mov_b64 s[24:25], 0
	s_waitcnt vmcnt(1)
	v_pk_add_f32 v[92:93], v[74:75], v[92:93]
	v_pk_add_f32 v[90:91], v[72:73], v[90:91]
	s_waitcnt vmcnt(0)
	v_pk_add_f32 v[96:97], v[70:71], v[96:97]
	v_pk_add_f32 v[94:95], v[68:69], v[94:95]
	global_store_dwordx4 v[86:87], v[90:93], off offset:512 nt
	global_store_dwordx4 v[86:87], v[94:97], off offset:528 nt
.LBB0_984:
	s_andn2_b64 vcc, exec, s[24:25]
	s_cbranch_vccnz .LBB0_988
	v_mul_f32_e32 v90, v81, v81
	v_mul_f32_e32 v91, v83, v83
	v_fmac_f32_e32 v90, v80, v80
	v_fmac_f32_e32 v91, v82, v82
	v_lshl_add_u64 v[88:89], v[88:89], 1, s[48:49]
	v_add_f32_e32 v90, v90, v91
	v_mul_f32_e32 v91, v77, v77
	v_mul_f32_e32 v92, v79, v79
	v_cvt_pk_bf16_f32 v80, v80, v81
	v_cvt_pk_bf16_f32 v81, v82, v83
	v_cvt_pk_bf16_f32 v82, v76, v77
	v_cvt_pk_bf16_f32 v83, v78, v79
	global_store_dwordx4 v[88:89], v[80:83], off nt
	v_fmac_f32_e32 v91, v76, v76
	v_fmac_f32_e32 v92, v78, v78
	global_load_dwordx4 v[76:79], v[86:87], off offset:528
	global_load_dwordx4 v[80:83], v[86:87], off offset:512
	v_add_f32_e32 v91, v91, v92
	v_add_f32_e32 v90, v90, v91
	s_waitcnt vmcnt(1)
	v_pk_add_f32 v[68:69], v[68:69], v[76:77]
	s_waitcnt vmcnt(0)
	v_pk_add_f32 v[74:75], v[74:75], v[82:83]
	v_pk_add_f32 v[72:73], v[72:73], v[80:81]
	v_mul_f32_e32 v77, v75, v75
	v_mul_f32_e32 v76, v73, v73
	v_pk_add_f32 v[70:71], v[70:71], v[78:79]
	v_fmac_f32_e32 v76, v72, v72
	v_fmac_f32_e32 v77, v74, v74
	v_add_f32_e32 v76, v76, v77
	v_mul_f32_e32 v77, v69, v69
	v_mul_f32_e32 v78, v71, v71
	global_store_dwordx4 v[86:87], v[72:75], off offset:512 nt
	global_store_dwordx4 v[86:87], v[68:71], off offset:528 nt
	v_fmac_f32_e32 v77, v68, v68
	v_fmac_f32_e32 v78, v70, v70
	v_cvt_pk_bf16_f32 v72, v72, v73
	v_cvt_pk_bf16_f32 v73, v74, v75
	v_cvt_pk_bf16_f32 v74, v68, v69
	v_add_u32_e32 v69, 64, v151
	v_add_f32_e32 v77, v77, v78
	v_cmp_lt_i32_e32 vcc, v150, v69
	v_add_f32_e32 v76, v76, v77
	v_add_f32_e32 v76, v90, v76
	v_cndmask_b32_e32 v68, v204, v150, vcc
	v_lshlrev_b32_e32 v68, 2, v68
	ds_bpermute_b32 v68, v68, v76
	v_cmp_lt_i32_e32 vcc, v149, v69
	v_cvt_pk_bf16_f32 v75, v70, v71
	global_store_dwordx4 v[88:89], v[72:75], off offset:256 nt
	s_waitcnt lgkmcnt(0)
	v_add_f32_e32 v68, v76, v68
	v_cndmask_b32_e32 v69, v204, v149, vcc
	v_lshlrev_b32_e32 v69, 2, v69
	ds_bpermute_b32 v69, v69, v68
	s_and_saveexec_b64 s[24:25], s[38:39]
	s_cbranch_execz .LBB0_987
	v_lshl_add_u64 v[70:71], v[84:85], 2, s[46:47]
	s_waitcnt lgkmcnt(0)
	v_add_f32_e32 v68, v68, v69
	global_atomic_add_f32 v[70:71], v68, off

.LBB0_988:
	v_add_u32_e32 v68, 0x80, v140
	s_waitcnt lgkmcnt(0)
	v_ashrrev_i32_e32 v69, 31, v68
	v_lshlrev_b64 v[70:71], 10, v[68:69]
	v_lshl_add_u64 v[72:73], v[70:71], 0, v[138:139]
	v_lshl_add_u64 v[70:71], v[72:73], 2, s[44:45]
	global_load_dwordx4 v[74:77], v[70:71], off
	global_load_dwordx4 v[78:81], v[70:71], off offset:16
	s_mov_b64 s[24:25], -1
	s_and_b64 vcc, exec, s[0:1]
	s_waitcnt vmcnt(1)
	v_pk_add_f32 v[66:67], v[66:67], v[76:77]
	v_pk_add_f32 v[64:65], v[64:65], v[74:75]
	s_waitcnt vmcnt(0)
	v_pk_add_f32 v[62:63], v[62:63], v[80:81]
	v_pk_add_f32 v[60:61], v[60:61], v[78:79]
	global_store_dwordx4 v[70:71], v[64:67], off nt
	global_store_dwordx4 v[70:71], v[60:63], off offset:16 nt
	s_cbranch_vccz .LBB0_990
	global_load_dwordx4 v[74:77], v[70:71], off offset:512
	global_load_dwordx4 v[78:81], v[70:71], off offset:528
	s_mov_b64 s[24:25], 0
	s_waitcnt vmcnt(1)
	v_pk_add_f32 v[76:77], v[58:59], v[76:77]
	v_pk_add_f32 v[74:75], v[56:57], v[74:75]
	s_waitcnt vmcnt(0)
	v_pk_add_f32 v[80:81], v[54:55], v[80:81]
	v_pk_add_f32 v[78:79], v[52:53], v[78:79]
	global_store_dwordx4 v[70:71], v[74:77], off offset:512 nt
	global_store_dwordx4 v[70:71], v[78:81], off offset:528 nt
.LBB0_990:
	s_andn2_b64 vcc, exec, s[24:25]
	s_cbranch_vccnz .LBB0_994
	v_mul_f32_e32 v74, v65, v65
	v_mul_f32_e32 v75, v67, v67
	v_fmac_f32_e32 v74, v64, v64
	v_fmac_f32_e32 v75, v66, v66
	v_lshl_add_u64 v[72:73], v[72:73], 1, s[48:49]
	v_add_f32_e32 v74, v74, v75
	v_mul_f32_e32 v75, v61, v61
	v_mul_f32_e32 v76, v63, v63
	v_cvt_pk_bf16_f32 v64, v64, v65
	v_cvt_pk_bf16_f32 v65, v66, v67
	v_cvt_pk_bf16_f32 v66, v60, v61
	v_cvt_pk_bf16_f32 v67, v62, v63
	global_store_dwordx4 v[72:73], v[64:67], off nt
	v_fmac_f32_e32 v75, v60, v60
	v_fmac_f32_e32 v76, v62, v62
	global_load_dwordx4 v[60:63], v[70:71], off offset:528
	global_load_dwordx4 v[64:67], v[70:71], off offset:512
	v_add_f32_e32 v75, v75, v76
	v_add_f32_e32 v74, v74, v75
	s_waitcnt vmcnt(1)
	v_pk_add_f32 v[52:53], v[52:53], v[60:61]
	s_waitcnt vmcnt(0)
	v_pk_add_f32 v[58:59], v[58:59], v[66:67]
	v_pk_add_f32 v[56:57], v[56:57], v[64:65]
	v_mul_f32_e32 v61, v59, v59
	v_mul_f32_e32 v60, v57, v57
	v_pk_add_f32 v[54:55], v[54:55], v[62:63]
	v_fmac_f32_e32 v60, v56, v56
	v_fmac_f32_e32 v61, v58, v58
	v_add_f32_e32 v60, v60, v61
	v_mul_f32_e32 v61, v53, v53
	v_mul_f32_e32 v62, v55, v55
	global_store_dwordx4 v[70:71], v[56:59], off offset:512 nt
	global_store_dwordx4 v[70:71], v[52:55], off offset:528 nt
	v_fmac_f32_e32 v61, v52, v52
	v_fmac_f32_e32 v62, v54, v54
	v_cvt_pk_bf16_f32 v56, v56, v57
	v_cvt_pk_bf16_f32 v57, v58, v59
	v_cvt_pk_bf16_f32 v58, v52, v53
	v_add_u32_e32 v53, 64, v151
	v_add_f32_e32 v61, v61, v62
	v_cmp_lt_i32_e32 vcc, v150, v53
	v_add_f32_e32 v60, v60, v61
	v_add_f32_e32 v60, v74, v60
	v_cndmask_b32_e32 v52, v204, v150, vcc
	v_lshlrev_b32_e32 v52, 2, v52
	ds_bpermute_b32 v52, v52, v60
	v_cmp_lt_i32_e32 vcc, v149, v53
	v_cvt_pk_bf16_f32 v59, v54, v55
	global_store_dwordx4 v[72:73], v[56:59], off offset:256 nt
	s_waitcnt lgkmcnt(0)
	v_add_f32_e32 v52, v60, v52
	v_cndmask_b32_e32 v53, v204, v149, vcc
	v_lshlrev_b32_e32 v53, 2, v53
	ds_bpermute_b32 v53, v53, v52
	s_and_saveexec_b64 s[24:25], s[38:39]
	s_cbranch_execz .LBB0_993
	v_lshl_add_u64 v[54:55], v[68:69], 2, s[46:47]
	s_waitcnt lgkmcnt(0)
	v_add_f32_e32 v52, v52, v53
	global_atomic_add_f32 v[54:55], v52, off

.LBB0_994:
	v_add_u32_e32 v52, 0x90, v140
	s_waitcnt lgkmcnt(0)
	v_ashrrev_i32_e32 v53, 31, v52
	v_lshlrev_b64 v[54:55], 10, v[52:53]
	v_lshl_add_u64 v[56:57], v[54:55], 0, v[138:139]
	v_lshl_add_u64 v[54:55], v[56:57], 2, s[44:45]
	global_load_dwordx4 v[58:61], v[54:55], off
	global_load_dwordx4 v[62:65], v[54:55], off offset:16
	s_mov_b64 s[24:25], -1
	s_and_b64 vcc, exec, s[0:1]
	s_waitcnt vmcnt(1)
	v_pk_add_f32 v[50:51], v[50:51], v[60:61]
	v_pk_add_f32 v[48:49], v[48:49], v[58:59]
	s_waitcnt vmcnt(0)
	v_pk_add_f32 v[46:47], v[46:47], v[64:65]
	v_pk_add_f32 v[44:45], v[44:45], v[62:63]
	global_store_dwordx4 v[54:55], v[48:51], off nt
	global_store_dwordx4 v[54:55], v[44:47], off offset:16 nt
	s_cbranch_vccz .LBB0_996
	global_load_dwordx4 v[58:61], v[54:55], off offset:512
	global_load_dwordx4 v[62:65], v[54:55], off offset:528
	s_mov_b64 s[24:25], 0
	s_waitcnt vmcnt(1)
	v_pk_add_f32 v[60:61], v[42:43], v[60:61]
	v_pk_add_f32 v[58:59], v[40:41], v[58:59]
	s_waitcnt vmcnt(0)
	v_pk_add_f32 v[64:65], v[38:39], v[64:65]
	v_pk_add_f32 v[62:63], v[36:37], v[62:63]
	global_store_dwordx4 v[54:55], v[58:61], off offset:512 nt
	global_store_dwordx4 v[54:55], v[62:65], off offset:528 nt
.LBB0_996:
	s_andn2_b64 vcc, exec, s[24:25]
	s_cbranch_vccnz .LBB0_1000
	v_mul_f32_e32 v58, v49, v49
	v_mul_f32_e32 v59, v51, v51
	v_fmac_f32_e32 v58, v48, v48
	v_fmac_f32_e32 v59, v50, v50
	v_lshl_add_u64 v[56:57], v[56:57], 1, s[48:49]
	v_add_f32_e32 v58, v58, v59
	v_mul_f32_e32 v59, v45, v45
	v_mul_f32_e32 v60, v47, v47
	v_cvt_pk_bf16_f32 v48, v48, v49
	v_cvt_pk_bf16_f32 v49, v50, v51
	v_cvt_pk_bf16_f32 v50, v44, v45
	v_cvt_pk_bf16_f32 v51, v46, v47
	global_store_dwordx4 v[56:57], v[48:51], off nt
	v_fmac_f32_e32 v59, v44, v44
	v_fmac_f32_e32 v60, v46, v46
	global_load_dwordx4 v[44:47], v[54:55], off offset:528
	global_load_dwordx4 v[48:51], v[54:55], off offset:512
	v_add_f32_e32 v59, v59, v60
	v_add_f32_e32 v58, v58, v59
	s_waitcnt vmcnt(1)
	v_pk_add_f32 v[36:37], v[36:37], v[44:45]
	s_waitcnt vmcnt(0)
	v_pk_add_f32 v[42:43], v[42:43], v[50:51]
	v_pk_add_f32 v[40:41], v[40:41], v[48:49]
	v_mul_f32_e32 v45, v43, v43
	v_mul_f32_e32 v44, v41, v41
	v_pk_add_f32 v[38:39], v[38:39], v[46:47]
	v_fmac_f32_e32 v44, v40, v40
	v_fmac_f32_e32 v45, v42, v42
	v_add_f32_e32 v44, v44, v45
	v_mul_f32_e32 v45, v37, v37
	v_mul_f32_e32 v46, v39, v39
	global_store_dwordx4 v[54:55], v[40:43], off offset:512 nt
	global_store_dwordx4 v[54:55], v[36:39], off offset:528 nt
	v_fmac_f32_e32 v45, v36, v36
	v_fmac_f32_e32 v46, v38, v38
	v_cvt_pk_bf16_f32 v40, v40, v41
	v_cvt_pk_bf16_f32 v41, v42, v43
	v_cvt_pk_bf16_f32 v42, v36, v37
	v_add_u32_e32 v37, 64, v151
	v_add_f32_e32 v45, v45, v46
	v_cmp_lt_i32_e32 vcc, v150, v37
	v_add_f32_e32 v44, v44, v45
	v_add_f32_e32 v44, v58, v44
	v_cndmask_b32_e32 v36, v204, v150, vcc
	v_lshlrev_b32_e32 v36, 2, v36
	ds_bpermute_b32 v36, v36, v44
	v_cmp_lt_i32_e32 vcc, v149, v37
	v_cvt_pk_bf16_f32 v43, v38, v39
	global_store_dwordx4 v[56:57], v[40:43], off offset:256 nt
	s_waitcnt lgkmcnt(0)
	v_add_f32_e32 v36, v44, v36
	v_cndmask_b32_e32 v37, v204, v149, vcc
	v_lshlrev_b32_e32 v37, 2, v37
	ds_bpermute_b32 v37, v37, v36
	s_and_saveexec_b64 s[24:25], s[38:39]
	s_cbranch_execz .LBB0_999
	v_lshl_add_u64 v[38:39], v[52:53], 2, s[46:47]
	s_waitcnt lgkmcnt(0)
	v_add_f32_e32 v36, v36, v37
	global_atomic_add_f32 v[38:39], v36, off

.LBB0_1000:
	v_add_u32_e32 v36, 0xa0, v140
	s_waitcnt lgkmcnt(0)
	v_ashrrev_i32_e32 v37, 31, v36
	v_lshlrev_b64 v[38:39], 10, v[36:37]
	v_lshl_add_u64 v[40:41], v[38:39], 0, v[138:139]
	v_lshl_add_u64 v[38:39], v[40:41], 2, s[44:45]
	global_load_dwordx4 v[42:45], v[38:39], off
	global_load_dwordx4 v[46:49], v[38:39], off offset:16
	s_mov_b64 s[24:25], -1
	s_and_b64 vcc, exec, s[0:1]
	s_waitcnt vmcnt(1)
	v_pk_add_f32 v[34:35], v[34:35], v[44:45]
	v_pk_add_f32 v[32:33], v[32:33], v[42:43]
	s_waitcnt vmcnt(0)
	v_pk_add_f32 v[30:31], v[30:31], v[48:49]
	v_pk_add_f32 v[28:29], v[28:29], v[46:47]
	global_store_dwordx4 v[38:39], v[32:35], off nt
	global_store_dwordx4 v[38:39], v[28:31], off offset:16 nt
	s_cbranch_vccz .LBB0_1002
	global_load_dwordx4 v[42:45], v[38:39], off offset:512
	global_load_dwordx4 v[46:49], v[38:39], off offset:528
	s_mov_b64 s[24:25], 0
	s_waitcnt vmcnt(1)
	v_pk_add_f32 v[44:45], v[26:27], v[44:45]
	v_pk_add_f32 v[42:43], v[24:25], v[42:43]
	s_waitcnt vmcnt(0)
	v_pk_add_f32 v[48:49], v[22:23], v[48:49]
	v_pk_add_f32 v[46:47], v[20:21], v[46:47]
	global_store_dwordx4 v[38:39], v[42:45], off offset:512 nt
	global_store_dwordx4 v[38:39], v[46:49], off offset:528 nt
.LBB0_1002:
	s_andn2_b64 vcc, exec, s[24:25]
	s_cbranch_vccnz .LBB0_1006
	v_mul_f32_e32 v42, v33, v33
	v_mul_f32_e32 v43, v35, v35
	v_fmac_f32_e32 v42, v32, v32
	v_fmac_f32_e32 v43, v34, v34
	v_lshl_add_u64 v[40:41], v[40:41], 1, s[48:49]
	v_add_f32_e32 v42, v42, v43
	v_mul_f32_e32 v43, v29, v29
	v_mul_f32_e32 v44, v31, v31
	v_cvt_pk_bf16_f32 v32, v32, v33
	v_cvt_pk_bf16_f32 v33, v34, v35
	v_cvt_pk_bf16_f32 v34, v28, v29
	v_cvt_pk_bf16_f32 v35, v30, v31
	global_store_dwordx4 v[40:41], v[32:35], off nt
	v_fmac_f32_e32 v43, v28, v28
	v_fmac_f32_e32 v44, v30, v30
	global_load_dwordx4 v[28:31], v[38:39], off offset:528
	global_load_dwordx4 v[32:35], v[38:39], off offset:512
	v_add_f32_e32 v43, v43, v44
	v_add_f32_e32 v42, v42, v43
	s_waitcnt vmcnt(1)
	v_pk_add_f32 v[20:21], v[20:21], v[28:29]
	s_waitcnt vmcnt(0)
	v_pk_add_f32 v[26:27], v[26:27], v[34:35]
	v_pk_add_f32 v[24:25], v[24:25], v[32:33]
	v_mul_f32_e32 v29, v27, v27
	v_mul_f32_e32 v28, v25, v25
	v_pk_add_f32 v[22:23], v[22:23], v[30:31]
	v_fmac_f32_e32 v28, v24, v24
	v_fmac_f32_e32 v29, v26, v26
	v_add_f32_e32 v28, v28, v29
	v_mul_f32_e32 v29, v21, v21
	v_mul_f32_e32 v30, v23, v23
	global_store_dwordx4 v[38:39], v[24:27], off offset:512 nt
	global_store_dwordx4 v[38:39], v[20:23], off offset:528 nt
	v_fmac_f32_e32 v29, v20, v20
	v_fmac_f32_e32 v30, v22, v22
	v_cvt_pk_bf16_f32 v24, v24, v25
	v_cvt_pk_bf16_f32 v25, v26, v27
	v_cvt_pk_bf16_f32 v26, v20, v21
	v_add_u32_e32 v21, 64, v151
	v_add_f32_e32 v29, v29, v30
	v_cmp_lt_i32_e32 vcc, v150, v21
	v_add_f32_e32 v28, v28, v29
	v_add_f32_e32 v28, v42, v28
	v_cndmask_b32_e32 v20, v204, v150, vcc
	v_lshlrev_b32_e32 v20, 2, v20
	ds_bpermute_b32 v20, v20, v28
	v_cmp_lt_i32_e32 vcc, v149, v21
	v_cvt_pk_bf16_f32 v27, v22, v23
	global_store_dwordx4 v[40:41], v[24:27], off offset:256 nt
	s_waitcnt lgkmcnt(0)
	v_add_f32_e32 v20, v28, v20
	v_cndmask_b32_e32 v21, v204, v149, vcc
	v_lshlrev_b32_e32 v21, 2, v21
	ds_bpermute_b32 v21, v21, v20
	s_and_saveexec_b64 s[24:25], s[38:39]
	s_cbranch_execz .LBB0_1005
	v_lshl_add_u64 v[22:23], v[36:37], 2, s[46:47]
	s_waitcnt lgkmcnt(0)
	v_add_f32_e32 v20, v20, v21
	global_atomic_add_f32 v[22:23], v20, off

.LBB0_1006:
	v_add_u32_e32 v20, 0xb0, v140
	s_waitcnt lgkmcnt(0)
	v_ashrrev_i32_e32 v21, 31, v20
	v_lshlrev_b64 v[22:23], 10, v[20:21]
	v_lshl_add_u64 v[24:25], v[22:23], 0, v[138:139]
	v_lshl_add_u64 v[22:23], v[24:25], 2, s[44:45]
	global_load_dwordx4 v[26:29], v[22:23], off
	global_load_dwordx4 v[30:33], v[22:23], off offset:16
	s_mov_b64 s[24:25], -1
	s_and_b64 vcc, exec, s[0:1]
	s_waitcnt vmcnt(1)
	v_pk_add_f32 v[18:19], v[18:19], v[28:29]
	v_pk_add_f32 v[16:17], v[16:17], v[26:27]
	s_waitcnt vmcnt(0)
	v_pk_add_f32 v[14:15], v[14:15], v[32:33]
	v_pk_add_f32 v[12:13], v[12:13], v[30:31]
	global_store_dwordx4 v[22:23], v[16:19], off nt
	global_store_dwordx4 v[22:23], v[12:15], off offset:16 nt
	s_cbranch_vccnz .LBB0_1009
	s_andn2_b64 vcc, exec, s[24:25]
	s_cbranch_vccz .LBB0_1010

.LBB0_1009:
	global_load_dwordx4 v[26:29], v[22:23], off offset:512
	global_load_dwordx4 v[30:33], v[22:23], off offset:528
	s_waitcnt vmcnt(1)
	v_pk_add_f32 v[28:29], v[10:11], v[28:29]
	v_pk_add_f32 v[26:27], v[8:9], v[26:27]
	s_waitcnt vmcnt(0)
	v_pk_add_f32 v[32:33], v[6:7], v[32:33]
	v_pk_add_f32 v[30:31], v[4:5], v[30:31]
	global_store_dwordx4 v[22:23], v[26:29], off offset:512 nt
	global_store_dwordx4 v[22:23], v[30:33], off offset:528 nt
	s_cbranch_execnz .LBB0_1008
.LBB0_1010:
	v_mul_f32_e32 v26, v17, v17
	v_mul_f32_e32 v27, v19, v19
	v_fmac_f32_e32 v26, v16, v16
	v_fmac_f32_e32 v27, v18, v18
	v_lshl_add_u64 v[24:25], v[24:25], 1, s[48:49]
	v_add_f32_e32 v26, v26, v27
	v_mul_f32_e32 v27, v13, v13
	v_mul_f32_e32 v28, v15, v15
	v_cvt_pk_bf16_f32 v16, v16, v17
	v_cvt_pk_bf16_f32 v17, v18, v19
	v_cvt_pk_bf16_f32 v18, v12, v13
	v_cvt_pk_bf16_f32 v19, v14, v15
	global_store_dwordx4 v[24:25], v[16:19], off nt
	v_fmac_f32_e32 v27, v12, v12
	v_fmac_f32_e32 v28, v14, v14
	global_load_dwordx4 v[12:15], v[22:23], off offset:528
	global_load_dwordx4 v[16:19], v[22:23], off offset:512
	v_add_f32_e32 v27, v27, v28
	v_add_f32_e32 v26, v26, v27
	s_waitcnt vmcnt(1)
	v_pk_add_f32 v[4:5], v[4:5], v[12:13]
	s_waitcnt vmcnt(0)
	v_pk_add_f32 v[10:11], v[10:11], v[18:19]
	v_pk_add_f32 v[8:9], v[8:9], v[16:17]
	v_mul_f32_e32 v13, v11, v11
	v_mul_f32_e32 v12, v9, v9
	v_pk_add_f32 v[6:7], v[6:7], v[14:15]
	v_fmac_f32_e32 v12, v8, v8
	v_fmac_f32_e32 v13, v10, v10
	v_add_f32_e32 v12, v12, v13
	v_mul_f32_e32 v13, v5, v5
	v_mul_f32_e32 v14, v7, v7
	global_store_dwordx4 v[22:23], v[8:11], off offset:512 nt
	global_store_dwordx4 v[22:23], v[4:7], off offset:528 nt
	v_fmac_f32_e32 v13, v4, v4
	v_fmac_f32_e32 v14, v6, v6
	v_cvt_pk_bf16_f32 v8, v8, v9
	v_cvt_pk_bf16_f32 v9, v10, v11
	v_cvt_pk_bf16_f32 v10, v4, v5
	v_add_u32_e32 v5, 64, v151
	v_add_f32_e32 v13, v13, v14
	v_cmp_lt_i32_e32 vcc, v150, v5
	v_add_f32_e32 v12, v12, v13
	v_add_f32_e32 v12, v26, v12
	v_cndmask_b32_e32 v4, v204, v150, vcc
	v_lshlrev_b32_e32 v4, 2, v4
	ds_bpermute_b32 v4, v4, v12
	v_cmp_lt_i32_e32 vcc, v149, v5
	v_cvt_pk_bf16_f32 v11, v6, v7
	global_store_dwordx4 v[24:25], v[8:11], off offset:256 nt
	s_waitcnt lgkmcnt(0)
	v_add_f32_e32 v4, v12, v4
	v_cndmask_b32_e32 v5, v204, v149, vcc
	v_lshlrev_b32_e32 v5, 2, v5
	ds_bpermute_b32 v5, v5, v4
	s_and_saveexec_b64 s[24:25], s[38:39]
	s_cbranch_execz .LBB0_1012
	v_lshl_add_u64 v[6:7], v[20:21], 2, s[46:47]
	s_waitcnt lgkmcnt(0)
	v_add_f32_e32 v4, v4, v5
	global_atomic_add_f32 v[6:7], v4, off
